# FFN-up epilogues: per-row rstd computed once per workgroup (row panel is invariant across its units), cached in LDS and reused instead of reloading and reducing ssq every unit
# speedup vs baseline: 1.0149x; 1.0149x over previous
; template <class Epi, class Sched, bool ALIGN_EPI = false, bool SP2 = false>
; __device__ __forceinline__ void gemm_phase(PG8_LAS unsigned char* lds, const Gemm g, const Sched& S, const Epi& E) {
;     ...
;     const int tid = tid_o, wid = __builtin_amdgcn_readfirstlane(tid >> 6), lane = tid & 63, wr = wid >> 2, wc = wid & 3, fr = lane & 15, fq = lane >> 4;
;     const int K = g.K, nt = K / BK;
;     unsigned voffA[2], voffB[2];
; #pragma unroll
;     for (int i = 0; i < 2; ++i) { int R, C; stage_rc(tid * 16 + i * 8192, R, C); const int Rb = Epi::PERM ? ((R & ~31) + perm32(R & 31)) : R;
;         voffA[i] = (unsigned)(R * K + C) * 2u; voffB[i] = (unsigned)(Rb * K + C) * 2u; }
;     const size_t kstep = (size_t)(BK * 2);
;     const size_t hstep = (size_t)HALF * K * 2;
;     const size_t tstep = 2 * hstep;
;     const unsigned ldsw = (unsigned)wid * 1024u;
;     const int aoff = lds_byte(wr * 64 + fr, fq * 8), boff = lds_byte(wc * 32 + fr, fq * 8);
;     ...
;     Unit cur, nxt; int ui = 0;
;     if (!S.next(0, cur)) return;
;     f32x4 acc[2][2][4][2];
; #pragma unroll
;     for (int a = 0; a < 2; ++a)
; #pragma unroll
;         for (int b = 0; b < 2; ++b)
; #pragma unroll
;             for (int m = 0; m < 4; ++m)
; #pragma unroll
;                 for (int n = 0; n < 2; ++n) acc[a][b][m][n] = (f32x4){0.f, 0.f, 0.f, 0.f};
;     bf16x8 At[4][2], B0[2][2], B1[2][2];
;     const char* cA = (const char*)g.A + (size_t)cur.pm * tstep; const char* cB = (const char*)g.Bt + (size_t)cur.pn * tstep;
;     S.a_ready(cur);
;     if constexpr (SP2) {
;         PG8_STAGE(PG8_SB(0, 0), cB, voffB); PG8_STAGE(PG8_SB(0, 1), cB + hstep, voffB); PG8_STAGE(PG8_SA(0, 0), cA, voffA); PG8_STAGE(PG8_SA(0, 1), cA + hstep, voffA);
;         if (wr == 1) PG8_BAR;
;         PG8_WAIT_V(2); PG8_BAR;
;         PG8_STAGE(PG8_SB(1, 0), cB + kstep, voffB); PG8_STAGE(PG8_SA(1, 0), cA + kstep, voffA); PG8_STAGE(PG8_SB(1, 1), cB + hstep + kstep, voffB);
;         PG8_WAIT_V(6); PG8_BAR;
;     } else {
;         PG8_STAGE(PG8_SB(0, 0), cB, voffB); PG8_STAGE(PG8_SA(0, 0), cA, voffA); PG8_STAGE(PG8_SB(0, 1), cB + hstep, voffB); PG8_STAGE(PG8_SA(0, 1), cA + hstep, voffA);
;         if (wr == 1) PG8_BAR;
;         PG8_WAIT_V(4); PG8_BAR;
;         PG8_STAGE(PG8_SB(1, 0), cB + kstep, voffB); PG8_STAGE(PG8_SA(1, 0), cA + kstep, voffA); PG8_STAGE(PG8_SB(1, 1), cB + hstep + kstep, voffB);
;         PG8_WAIT_V(6); PG8_BAR;
.LBB0_121:
	s_lshl_b32 s8, s8, 5
	s_and_b32 s66, s8, 0x60
	s_mov_b64 s[8:9], 0x80
	s_add_i32 m0, s15, 0x18000
	v_lshl_add_u64 v[6:7], v[6:7], 0, s[8:9]
	s_lshl_b32 s11, s10, 13
	s_lshl_b32 s67, s66, 7
	s_waitcnt vmcnt(2)
	s_barrier
	global_load_lds_dwordx4 v[6:7], off
	v_lshl_add_u64 v[4:5], v[4:5], 0, s[8:9]
	s_add_i32 m0, s15, 0x1a000
	s_add_i32 s69, s15, 0x8000
	s_add_i32 s80, s15, 0xa000
	global_load_lds_dwordx4 v[4:5], off
	v_lshl_add_u64 v[0:1], v[0:1], 0, s[8:9]
	s_mov_b32 m0, s69
	s_add_u32 s12, s92, 0x80080
	global_load_lds_dwordx4 v[0:1], off
	v_lshl_add_u64 v[0:1], v[2:3], 0, s[8:9]
	s_mov_b32 m0, s80
	s_addc_u32 s13, s93, 0
	global_load_lds_dwordx4 v[0:1], off
	s_add_i32 m0, s15, 0x1c000
	v_lshl_add_u64 v[0:1], s[12:13], 0, v[132:133]
	global_load_lds_dwordx4 v[0:1], off
	v_lshl_add_u64 v[0:1], s[12:13], 0, v[128:129]
	s_add_i32 m0, s15, 0x1e000
	s_cmpk_lt_u32 s5, 0x100
	global_load_lds_dwordx4 v[0:1], off
	v_lshrrev_b32_e32 v1, 1, v9
	v_and_b32_e32 v2, 24, v1
	v_and_b32_e32 v0, 15, v9
	v_lshlrev_b32_e32 v1, 1, v2
	v_lshl_or_b32 v155, s10, 6, v0
	v_lshl_or_b32 v0, v0, 6, v1
	v_lshlrev_b32_e32 v1, 2, v9
	v_and_b32_e32 v1, 32, v1
	v_bitop3_b32 v3, v0, s11, v1 bitop3:0xde
	v_bitop3_b32 v159, v0, s67, v1 bitop3:0xde
	v_lshlrev_b32_e32 v0, 2, v2
	v_mov_b32_e32 v1, v133
	v_lshl_add_u64 v[136:137], s[58:59], 0, v[0:1]
	v_lshlrev_b32_e32 v0, 15, v13
	v_and_b32_e32 v0, 0xffff0000, v0
	v_lshl_add_u32 v0, v12, 12, v0
	v_and_b32_e32 v1, 1, v13
	v_lshl_or_b32 v0, v1, 6, v0
	v_lshl_add_u32 v138, v14, 1, v0
	v_lshlrev_b32_e32 v0, 15, v8
	v_and_b32_e32 v0, 0xffff0000, v0
	s_waitcnt vmcnt(6)
	v_lshl_add_u32 v0, v10, 12, v0
	v_and_b32_e32 v1, 1, v8
	s_cselect_b64 s[10:11], -1, 0
	v_lshl_or_b32 v0, v1, 6, v0
	s_add_i32 s81, 0, 0x10000
	s_add_i32 s89, 0, 0x14000
	s_sext_i32_i16 s97, s4
	v_or_b32_e32 v163, s66, v2
	v_mov_b32_e32 v139, v133
	v_lshl_add_u32 v140, v11, 1, v0
	v_mov_b32_e32 v141, v133
	v_mov_b64_e32 v[142:143], 0x580
	v_mov_b64_e32 v[144:145], 0x57f
	v_add_u32_e32 v167, s81, v159
	v_add_u32_e32 v173, s89, v159
	v_add_u32_e32 v175, 0, v3
	v_mbcnt_hi_u32_b32 v176, -1, v216
	v_mov_b32_e32 v177, 0x358637bd
	s_movk_i32 s96, 0x2c00
	s_barrier
	s_mov_b32 s100, 0
	s_branch .LBB0_124

; __device__ __forceinline__ void rows_rstd(const float* ssq, int row0, int fq, float scale, float (&rs)[2][4]) {
;     f32x4 pa[2][4], pb[2][4];
; #pragma unroll
;     for (int ai = 0; ai < 2; ++ai)
; #pragma unroll
;         for (int m = 0; m < 4; ++m) { const f32x4* p = (const f32x4*)(ssq + (size_t)(row0 + ai * HALF + m * 16) * 32 + 8 * fq); pa[ai][m] = p[0]; pb[ai][m] = p[1]; }
; #pragma unroll
;     for (int ai = 0; ai < 2; ++ai)
; #pragma unroll
;         for (int m = 0; m < 4; ++m) { const f32x4 a = pa[ai][m], c = pb[ai][m]; float s = ((a[0] + a[1]) + (a[2] + a[3])) + ((c[0] + c[1]) + (c[2] + c[3]));
;             s += __shfl_xor(s, 16); s += __shfl_xor(s, 32); rs[ai][m] = __builtin_amdgcn_rsqf(s * (1.0f / DMODEL) + RMS_EPS) * scale; }
;     __device__ __forceinline__ void operator()(const f32x4 (&acc)[2][2][4][2], const Unit& u, int wr, int wc, int fr, int fq) const {
;         const int row0 = u.pm * BM + wr * 64 + fr, col0 = u.pn * HALF + wc * 32 + 8 * fq;
;         float rs[2][4];
;         rows_rstd(ssq, row0, fq, 1.0f, rs);
.LBB0_130:
	s_cmp_lg_u32 s100, 0
	s_cbranch_scc1 .Lrc1_fast
	v_lshrrev_b32_e32 v251, 6, v222
	v_and_b32_e32 v250, 15, v222
	v_lshl_or_b32 v251, v251, 4, v250
	v_lshlrev_b32_e32 v251, 5, v251
	v_add_u32_e32 v251, 0x20000, v251
	v_lshl_add_u32 v168, s88, 8, v155
	v_ashrrev_i32_e32 v169, 31, v168
	v_lshlrev_b64 v[146:147], 7, v[168:169]
	v_lshl_add_u64 v[146:147], v[136:137], 0, v[146:147]
	global_load_dwordx4 v[178:181], v[146:147], off
	global_load_dwordx4 v[182:185], v[146:147], off offset:16
	v_or_b32_e32 v164, 16, v168
	v_ashrrev_i32_e32 v165, 31, v164
	v_lshlrev_b64 v[146:147], 7, v[164:165]
	v_or_b32_e32 v160, 32, v168
	v_lshl_add_u64 v[146:147], v[136:137], 0, v[146:147]
	v_ashrrev_i32_e32 v161, 31, v160
	global_load_dwordx4 v[186:189], v[146:147], off
	global_load_dwordx4 v[190:193], v[146:147], off offset:16
	v_lshlrev_b64 v[146:147], 7, v[160:161]
	v_lshl_add_u64 v[146:147], v[136:137], 0, v[146:147]
	global_load_dwordx4 v[194:197], v[146:147], off
	global_load_dwordx4 v[198:201], v[146:147], off offset:16
	v_or_b32_e32 v156, 48, v168
	v_ashrrev_i32_e32 v157, 31, v156
	v_lshlrev_b64 v[146:147], 7, v[156:157]
	v_lshl_add_u64 v[146:147], v[136:137], 0, v[146:147]
	global_load_dwordx4 v[202:205], v[146:147], off
	global_load_dwordx4 v[206:209], v[146:147], off offset:16
	v_add_u32_e32 v152, 0x80, v168
	v_ashrrev_i32_e32 v153, 31, v152
	v_lshlrev_b64 v[210:211], 7, v[152:153]
	v_lshl_add_u64 v[214:215], v[136:137], 0, v[210:211]
	global_load_dwordx4 v[210:213], v[214:215], off
	global_load_dwordx4 v[218:221], v[214:215], off offset:16
	v_and_b32_e32 v147, 64, v176
	v_add_u32_e32 v150, 0x90, v168
	v_add_u32_e32 v148, 0xa0, v168
	v_add_u32_e32 v146, 0xb0, v168
	v_add_u32_e32 v158, 64, v147
	v_ashrrev_i32_e32 v151, 31, v150
	v_ashrrev_i32_e32 v149, 31, v148
	v_ashrrev_i32_e32 v147, 31, v146
	v_lshlrev_b64 v[214:215], 7, v[150:151]
	v_lshlrev_b64 v[224:225], 7, v[148:149]
	v_lshlrev_b64 v[226:227], 7, v[146:147]
	v_lshl_add_u64 v[214:215], v[136:137], 0, v[214:215]
	v_lshl_add_u64 v[236:237], v[136:137], 0, v[224:225]
	v_lshl_add_u64 v[244:245], v[136:137], 0, v[226:227]
	global_load_dwordx4 v[224:227], v[214:215], off
	global_load_dwordx4 v[228:231], v[214:215], off offset:16
	global_load_dwordx4 v[232:235], v[236:237], off
	s_nop 0
	global_load_dwordx4 v[236:239], v[236:237], off offset:16
	s_nop 0
	global_load_dwordx4 v[240:243], v[244:245], off
	s_nop 0
	global_load_dwordx4 v[244:247], v[244:245], off offset:16
	v_xor_b32_e32 v154, 16, v176
	v_cmp_lt_i32_e32 vcc, v154, v158
	v_xor_b32_e32 v157, 32, v176
	v_lshl_or_b32 v170, s97, 7, v163
	v_cndmask_b32_e32 v153, v176, v154, vcc
	v_lshlrev_b32_e32 v147, 2, v153
	v_cmp_lt_i32_e32 vcc, v157, v158
	v_ashrrev_i32_e32 v171, 31, v170
	s_waitcnt vmcnt(0)
	v_mov_b32_e32 v214, v178
	v_mov_b32_e32 v215, v182
	v_mov_b32_e32 v182, v179
	v_mov_b32_e32 v178, v180
	v_mov_b32_e32 v179, v184
	v_mov_b32_e32 v184, v181
	v_pk_add_f32 v[180:181], v[214:215], v[182:183]
	v_pk_add_f32 v[178:179], v[178:179], v[184:185]
	v_mov_b32_e32 v182, v186
	v_pk_add_f32 v[178:179], v[180:181], v[178:179]
	v_mov_b32_e32 v183, v190
	v_add_f32_e32 v151, v178, v179
	ds_bpermute_b32 v153, v147, v151
	v_mov_b32_e32 v190, v187
	v_mov_b32_e32 v184, v188
	v_mov_b32_e32 v185, v192
	v_mov_b32_e32 v192, v189
	v_pk_add_f32 v[180:181], v[182:183], v[190:191]
	v_pk_add_f32 v[182:183], v[184:185], v[192:193]
	v_cndmask_b32_e32 v154, v176, v157, vcc
	v_mov_b32_e32 v186, v194
	v_mov_b32_e32 v187, v198
	v_mov_b32_e32 v198, v195
	v_mov_b32_e32 v188, v196
	v_mov_b32_e32 v189, v200
	v_mov_b32_e32 v200, v197
	v_pk_add_f32 v[178:179], v[180:181], v[182:183]
	v_lshlrev_b32_e32 v149, 2, v154
	v_pk_add_f32 v[184:185], v[186:187], v[198:199]
	v_pk_add_f32 v[186:187], v[188:189], v[200:201]
	v_add_f32_e32 v154, v178, v179
	s_waitcnt lgkmcnt(0)
	v_add_f32_e32 v151, v151, v153
	v_pk_add_f32 v[180:181], v[184:185], v[186:187]
	ds_bpermute_b32 v158, v147, v154
	ds_bpermute_b32 v153, v149, v151
	v_add_f32_e32 v157, v180, v181
	ds_bpermute_b32 v161, v147, v157
	v_mov_b32_e32 v178, v202
	v_mov_b32_e32 v179, v206
	v_mov_b32_e32 v206, v203
	v_mov_b32_e32 v182, v204
	v_mov_b32_e32 v183, v208
	v_mov_b32_e32 v208, v205
	s_waitcnt lgkmcnt(2)
	v_add_f32_e32 v154, v154, v158
	s_waitcnt lgkmcnt(1)
	v_add_f32_e32 v151, v151, v153
	v_pk_add_f32 v[178:179], v[178:179], v[206:207]
	v_pk_add_f32 v[182:183], v[182:183], v[208:209]
	ds_bpermute_b32 v158, v149, v154
	v_fmamk_f32 v151, v151, 0x3a000000, v177
	v_pk_add_f32 v[178:179], v[178:179], v[182:183]
	s_waitcnt lgkmcnt(1)
	v_add_f32_e32 v157, v157, v161
	v_rsq_f32_e32 v180, v151
	v_add_f32_e32 v151, v178, v179
	ds_bpermute_b32 v161, v149, v157
	ds_bpermute_b32 v153, v147, v151
	v_mov_b32_e32 v182, v210
	v_mov_b32_e32 v183, v218
	v_mov_b32_e32 v218, v211
	v_mov_b32_e32 v184, v212
	v_mov_b32_e32 v185, v220
	v_mov_b32_e32 v220, v213
	s_waitcnt lgkmcnt(2)
	v_add_f32_e32 v154, v154, v158
	v_pk_add_f32 v[182:183], v[182:183], v[218:219]
	v_pk_add_f32 v[184:185], v[184:185], v[220:221]
	v_fmamk_f32 v154, v154, 0x3a000000, v177
	v_pk_add_f32 v[182:183], v[182:183], v[184:185]
	v_rsq_f32_e32 v178, v154
	s_waitcnt lgkmcnt(1)
	v_add_f32_e32 v154, v157, v161
	s_waitcnt lgkmcnt(0)
	v_add_f32_e32 v151, v151, v153
	v_add_f32_e32 v157, v182, v183
	ds_bpermute_b32 v153, v149, v151
	ds_bpermute_b32 v158, v147, v157
	v_fmamk_f32 v154, v154, 0x3a000000, v177
	v_mov_b32_e32 v182, v224
	v_mov_b32_e32 v183, v228
	s_waitcnt lgkmcnt(1)
	v_add_f32_e32 v151, v151, v153
	s_waitcnt lgkmcnt(0)
; __device__ __forceinline__ unsigned cvt_pk_bf16(float lo, float hi) { f32x2 v = {lo, hi}; bf16x2_t b = __builtin_convertvector(v, bf16x2_t); return __builtin_bit_cast(unsigned, b); }
; __device__ __forceinline__ float silu_f(float x) { return x * __builtin_amdgcn_rcpf(1.0f + __builtin_amdgcn_exp2f(-x * LOG2E)); }
; __device__ __forceinline__ void rows_rstd(const float* ssq, int row0, int fq, float scale, float (&rs)[2][4]) {
;     ...
;         for (int m = 0; m < 4; ++m) { const f32x4 a = pa[ai][m], c = pb[ai][m]; float s = ((a[0] + a[1]) + (a[2] + a[3])) + ((c[0] + c[1]) + (c[2] + c[3]));
;             s += __shfl_xor(s, 16); s += __shfl_xor(s, 32); rs[ai][m] = __builtin_amdgcn_rsqf(s * (1.0f / DMODEL) + RMS_EPS) * scale; }
;     __device__ __forceinline__ void operator()(const f32x4 (&acc)[2][2][4][2], const Unit& u, int wr, int wc, int fr, int fq) const {
;     ...
;             for (int m = 0; m < 4; ++m) { const int row = row0 + ai * HALF + m * 16; const float r = rs[ai][m];
;                 const f32x4 g0 = acc[ai][0][m][0] * r, g1 = acc[ai][0][m][1] * r, u0 = acc[ai][1][m][0] * r, u1 = acc[ai][1][m][1] * r;
;                 u32x4 w;
;                 w.x = cvt_pk_bf16(silu_f(g0[0]) * u0[0], silu_f(g0[1]) * u0[1]); w.y = cvt_pk_bf16(silu_f(g0[2]) * u0[2], silu_f(g0[3]) * u0[3]);
;                 w.z = cvt_pk_bf16(silu_f(g1[0]) * u1[0], silu_f(g1[1]) * u1[1]); w.w = cvt_pk_bf16(silu_f(g1[2]) * u1[2], silu_f(g1[3]) * u1[3]);
;                 *(u32x4*)(O + (size_t)row * ldo + col0) = w; }
	v_add_f32_e32 v153, v157, v158
	v_mov_b32_e32 v228, v225
	v_mov_b32_e32 v184, v226
	v_mov_b32_e32 v185, v230
	v_mov_b32_e32 v230, v227
	v_rsq_f32_e32 v174, v154
	ds_bpermute_b32 v154, v149, v153
	v_pk_add_f32 v[182:183], v[182:183], v[228:229]
	v_pk_add_f32 v[184:185], v[184:185], v[230:231]
	v_fmamk_f32 v151, v151, 0x3a000000, v177
	v_pk_add_f32 v[182:183], v[182:183], v[184:185]
	v_mov_b32_e32 v184, v234
	v_add_f32_e32 v157, v182, v183
	v_mov_b32_e32 v182, v232
	v_mov_b32_e32 v183, v236
	v_mov_b32_e32 v236, v233
	v_mov_b32_e32 v185, v238
	v_mov_b32_e32 v238, v235
	ds_bpermute_b32 v158, v147, v157
	v_pk_add_f32 v[182:183], v[182:183], v[236:237]
	v_pk_add_f32 v[184:185], v[184:185], v[238:239]
	v_rsq_f32_e32 v172, v151
	v_pk_add_f32 v[182:183], v[182:183], v[184:185]
	s_waitcnt lgkmcnt(1)
	v_add_f32_e32 v151, v153, v154
	v_add_f32_e32 v154, v182, v183
	v_mov_b32_e32 v182, v240
	v_mov_b32_e32 v183, v244
	v_mov_b32_e32 v244, v241
	v_mov_b32_e32 v184, v242
	v_mov_b32_e32 v185, v246
	v_mov_b32_e32 v246, v243
	v_pk_add_f32 v[182:183], v[182:183], v[244:245]
	v_pk_add_f32 v[184:185], v[184:185], v[246:247]
	v_fmamk_f32 v151, v151, 0x3a000000, v177
	v_pk_add_f32 v[182:183], v[182:183], v[184:185]
	v_rsq_f32_e32 v166, v151
	s_waitcnt lgkmcnt(0)
	v_add_f32_e32 v151, v157, v158
	v_add_f32_e32 v158, v182, v183
	ds_bpermute_b32 v153, v149, v151
	ds_bpermute_b32 v157, v147, v154
	ds_bpermute_b32 v147, v147, v158
	ds_write_b32 v251, v180 offset:0
	v_pk_mul_f32 v[124:125], v[124:125], v[180:181] op_sel_hi:[1,0]
	v_pk_mul_f32 v[126:127], v[126:127], v[180:181] op_sel_hi:[1,0]
	s_waitcnt lgkmcnt(2)
	v_add_f32_e32 v151, v151, v153
	s_waitcnt lgkmcnt(1)
	v_add_f32_e32 v153, v154, v157
	s_waitcnt lgkmcnt(0)
	v_add_f32_e32 v147, v158, v147
	ds_bpermute_b32 v154, v149, v153
	ds_bpermute_b32 v149, v149, v147
	v_fmamk_f32 v151, v151, 0x3a000000, v177
	v_rsq_f32_e32 v162, v151
	v_pk_mul_f32 v[122:123], v[122:123], v[180:181] op_sel_hi:[1,0]
	s_waitcnt lgkmcnt(1)
	v_add_f32_e32 v151, v153, v154
	s_waitcnt lgkmcnt(0)
	v_add_f32_e32 v147, v147, v149
	v_fmamk_f32 v147, v147, 0x3a000000, v177
	v_rsq_f32_e32 v154, v147
	v_mul_f32_e32 v147, 0xbfb8aa3b, v124
	v_exp_f32_e32 v147, v147
	v_mul_f32_e32 v149, 0xbfb8aa3b, v125
	v_exp_f32_e32 v149, v149
	v_fmamk_f32 v151, v151, 0x3a000000, v177
	v_add_f32_e32 v147, 1.0, v147
	v_pk_mul_f32 v[120:121], v[120:121], v[180:181] op_sel_hi:[1,0]
	v_pk_mul_f32 v[118:119], v[118:119], v[180:181] op_sel_hi:[1,0]
	v_pk_mul_f32 v[116:117], v[116:117], v[180:181] op_sel_hi:[1,0]
	v_pk_mul_f32 v[114:115], v[114:115], v[180:181] op_sel_hi:[1,0]
	v_pk_mul_f32 v[112:113], v[112:113], v[180:181] op_sel_hi:[1,0]
	v_rcp_f32_e32 v180, v147
	v_add_f32_e32 v147, 1.0, v149
	v_mul_f32_e32 v149, 0xbfb8aa3b, v126
	v_rsq_f32_e32 v158, v151
	v_exp_f32_e32 v149, v149
	v_mul_f32_e32 v151, 0xbfb8aa3b, v127
	v_exp_f32_e32 v151, v151
	v_rcp_f32_e32 v181, v147
	v_add_f32_e32 v147, 1.0, v149
	v_rcp_f32_e32 v182, v147
	v_add_f32_e32 v147, 1.0, v151
	v_rcp_f32_e32 v183, v147
	v_pk_mul_f32 v[124:125], v[124:125], v[180:181]
	ds_write_b32 v251, v178 offset:4
	v_pk_mul_f32 v[108:109], v[108:109], v[178:179] op_sel_hi:[1,0]
	v_pk_mul_f32 v[116:117], v[116:117], v[124:125]
	v_pk_mul_f32 v[124:125], v[126:127], v[182:183]
	v_cvt_pk_bf16_f32 v116, v116, v117
	v_mul_f32_e32 v117, 0xbfb8aa3b, v120
	v_pk_mul_f32 v[118:119], v[118:119], v[124:125]
	v_exp_f32_e32 v124, v117
	v_mul_f32_e32 v117, 0xbfb8aa3b, v121
	v_exp_f32_e32 v125, v117
	v_cvt_pk_bf16_f32 v117, v118, v119
	v_add_f32_e32 v118, 1.0, v124
	v_mul_f32_e32 v124, 0xbfb8aa3b, v122
	v_add_f32_e32 v119, 1.0, v125
	v_mul_f32_e32 v125, 0xbfb8aa3b, v123
	v_exp_f32_e32 v124, v124
	v_exp_f32_e32 v125, v125
	v_rcp_f32_e32 v118, v118
	v_rcp_f32_e32 v119, v119
	v_add_f32_e32 v124, 1.0, v124
	v_add_f32_e32 v125, 1.0, v125
	v_rcp_f32_e32 v124, v124
	v_rcp_f32_e32 v125, v125
	v_pk_mul_f32 v[118:119], v[120:121], v[118:119]
	v_pk_mul_f32 v[110:111], v[110:111], v[178:179] op_sel_hi:[1,0]
	v_pk_mul_f32 v[112:113], v[112:113], v[118:119]
	v_pk_mul_f32 v[100:101], v[100:101], v[178:179] op_sel_hi:[1,0]
	v_cvt_pk_bf16_f32 v118, v112, v113
	v_pk_mul_f32 v[112:113], v[122:123], v[124:125]
	v_pk_mul_f32 v[104:105], v[104:105], v[178:179] op_sel_hi:[1,0]
	v_pk_mul_f32 v[112:113], v[114:115], v[112:113]
	v_lshlrev_b64 v[114:115], 1, v[170:171]
	v_cvt_pk_bf16_f32 v119, v112, v113
	v_mov_b64_e32 v[112:113], s[38:39]
	v_mad_i64_i32 v[120:121], s[12:13], v168, s96, v[112:113]
	v_lshl_add_u64 v[120:121], v[120:121], 0, v[114:115]
	global_store_dwordx4 v[120:121], v[116:119], off
	v_pk_mul_f32 v[102:103], v[102:103], v[178:179] op_sel_hi:[1,0]
	v_pk_mul_f32 v[106:107], v[106:107], v[178:179] op_sel_hi:[1,0]
	v_pk_mul_f32 v[116:117], v[98:99], v[178:179] op_sel_hi:[1,0]
	v_mul_f32_e32 v98, 0xbfb8aa3b, v108
	v_exp_f32_e32 v118, v98
	v_mul_f32_e32 v98, 0xbfb8aa3b, v109
	v_exp_f32_e32 v119, v98
	v_pk_mul_f32 v[98:99], v[96:97], v[178:179] op_sel_hi:[1,0]
	v_add_f32_e32 v96, 1.0, v118
	v_mul_f32_e32 v118, 0xbfb8aa3b, v110
	v_add_f32_e32 v97, 1.0, v119
	v_mul_f32_e32 v119, 0xbfb8aa3b, v111
	v_exp_f32_e32 v118, v118
	v_exp_f32_e32 v119, v119
	v_rcp_f32_e32 v96, v96
	v_rcp_f32_e32 v97, v97
	v_add_f32_e32 v118, 1.0, v118
	v_add_f32_e32 v119, 1.0, v119
	v_rcp_f32_e32 v118, v118
	v_rcp_f32_e32 v119, v119
	v_pk_mul_f32 v[96:97], v[108:109], v[96:97]
	ds_write_b32 v251, v174 offset:8
	v_pk_mul_f32 v[92:93], v[92:93], v[174:175] op_sel_hi:[1,0]
	v_pk_mul_f32 v[96:97], v[100:101], v[96:97]
	v_pk_mul_f32 v[100:101], v[110:111], v[118:119]
	v_cvt_pk_bf16_f32 v96, v96, v97
	v_mul_f32_e32 v97, 0xbfb8aa3b, v104
	v_pk_mul_f32 v[100:101], v[102:103], v[100:101]
; __device__ __forceinline__ unsigned cvt_pk_bf16(float lo, float hi) { f32x2 v = {lo, hi}; bf16x2_t b = __builtin_convertvector(v, bf16x2_t); return __builtin_bit_cast(unsigned, b); }
; __device__ __forceinline__ float silu_f(float x) { return x * __builtin_amdgcn_rcpf(1.0f + __builtin_amdgcn_exp2f(-x * LOG2E)); }
;     __device__ __forceinline__ void operator()(const f32x4 (&acc)[2][2][4][2], const Unit& u, int wr, int wc, int fr, int fq) const {
;     ...
;             for (int m = 0; m < 4; ++m) { const int row = row0 + ai * HALF + m * 16; const float r = rs[ai][m];
;                 const f32x4 g0 = acc[ai][0][m][0] * r, g1 = acc[ai][0][m][1] * r, u0 = acc[ai][1][m][0] * r, u1 = acc[ai][1][m][1] * r;
;                 u32x4 w;
;                 w.x = cvt_pk_bf16(silu_f(g0[0]) * u0[0], silu_f(g0[1]) * u0[1]); w.y = cvt_pk_bf16(silu_f(g0[2]) * u0[2], silu_f(g0[3]) * u0[3]);
;                 w.z = cvt_pk_bf16(silu_f(g1[0]) * u1[0], silu_f(g1[1]) * u1[1]); w.w = cvt_pk_bf16(silu_f(g1[2]) * u1[2], silu_f(g1[3]) * u1[3]);
;                 *(u32x4*)(O + (size_t)row * ldo + col0) = w; }
	v_exp_f32_e32 v102, v97
	v_mul_f32_e32 v97, 0xbfb8aa3b, v105
	v_exp_f32_e32 v103, v97
	v_cvt_pk_bf16_f32 v97, v100, v101
	v_add_f32_e32 v100, 1.0, v102
	v_mul_f32_e32 v102, 0xbfb8aa3b, v106
	v_add_f32_e32 v101, 1.0, v103
	v_mul_f32_e32 v103, 0xbfb8aa3b, v107
	v_exp_f32_e32 v102, v102
	v_exp_f32_e32 v103, v103
	v_rcp_f32_e32 v100, v100
	v_rcp_f32_e32 v101, v101
	v_add_f32_e32 v102, 1.0, v102
	v_add_f32_e32 v103, 1.0, v103
	v_rcp_f32_e32 v102, v102
	v_rcp_f32_e32 v103, v103
	v_pk_mul_f32 v[100:101], v[104:105], v[100:101]
	v_pk_mul_f32 v[94:95], v[94:95], v[174:175] op_sel_hi:[1,0]
	v_pk_mul_f32 v[98:99], v[98:99], v[100:101]
	v_pk_mul_f32 v[100:101], v[106:107], v[102:103]
	v_cvt_pk_bf16_f32 v98, v98, v99
	v_pk_mul_f32 v[100:101], v[116:117], v[100:101]
	v_pk_mul_f32 v[84:85], v[84:85], v[174:175] op_sel_hi:[1,0]
	v_cvt_pk_bf16_f32 v99, v100, v101
	v_mad_i64_i32 v[100:101], s[12:13], v164, s96, v[112:113]
	v_lshl_add_u64 v[100:101], v[100:101], 0, v[114:115]
	global_store_dwordx4 v[100:101], v[96:99], off
	v_pk_mul_f32 v[88:89], v[88:89], v[174:175] op_sel_hi:[1,0]
	v_pk_mul_f32 v[86:87], v[86:87], v[174:175] op_sel_hi:[1,0]
	v_pk_mul_f32 v[96:97], v[82:83], v[174:175] op_sel_hi:[1,0]
	v_mul_f32_e32 v82, 0xbfb8aa3b, v92
	v_exp_f32_e32 v98, v82
	v_mul_f32_e32 v82, 0xbfb8aa3b, v93
	v_exp_f32_e32 v99, v82
	v_pk_mul_f32 v[82:83], v[80:81], v[174:175] op_sel_hi:[1,0]
	v_add_f32_e32 v80, 1.0, v98
	v_mul_f32_e32 v98, 0xbfb8aa3b, v94
	v_add_f32_e32 v81, 1.0, v99
	v_mul_f32_e32 v99, 0xbfb8aa3b, v95
	v_exp_f32_e32 v98, v98
	v_exp_f32_e32 v99, v99
	v_rcp_f32_e32 v80, v80
	v_rcp_f32_e32 v81, v81
	v_add_f32_e32 v98, 1.0, v98
	v_add_f32_e32 v99, 1.0, v99
	v_rcp_f32_e32 v98, v98
	v_rcp_f32_e32 v99, v99
	v_pk_mul_f32 v[80:81], v[92:93], v[80:81]
	v_pk_mul_f32 v[90:91], v[90:91], v[174:175] op_sel_hi:[1,0]
	v_pk_mul_f32 v[80:81], v[84:85], v[80:81]
	v_pk_mul_f32 v[84:85], v[94:95], v[98:99]
	v_cvt_pk_bf16_f32 v80, v80, v81
	v_mul_f32_e32 v81, 0xbfb8aa3b, v88
	v_pk_mul_f32 v[84:85], v[86:87], v[84:85]
	v_exp_f32_e32 v86, v81
	v_mul_f32_e32 v81, 0xbfb8aa3b, v89
	v_exp_f32_e32 v87, v81
	v_cvt_pk_bf16_f32 v81, v84, v85
	v_add_f32_e32 v84, 1.0, v86
	v_mul_f32_e32 v86, 0xbfb8aa3b, v90
	v_add_f32_e32 v85, 1.0, v87
	v_mul_f32_e32 v87, 0xbfb8aa3b, v91
	v_exp_f32_e32 v86, v86
	v_exp_f32_e32 v87, v87
	v_rcp_f32_e32 v84, v84
	v_rcp_f32_e32 v85, v85
	v_add_f32_e32 v86, 1.0, v86
	v_add_f32_e32 v87, 1.0, v87
	v_rcp_f32_e32 v86, v86
	v_rcp_f32_e32 v87, v87
	v_pk_mul_f32 v[84:85], v[88:89], v[84:85]
	ds_write_b32 v251, v172 offset:12
	v_pk_mul_f32 v[76:77], v[76:77], v[172:173] op_sel_hi:[1,0]
	v_pk_mul_f32 v[82:83], v[82:83], v[84:85]
	v_pk_mul_f32 v[84:85], v[90:91], v[86:87]
	v_cvt_pk_bf16_f32 v82, v82, v83
	v_pk_mul_f32 v[84:85], v[96:97], v[84:85]
	v_pk_mul_f32 v[78:79], v[78:79], v[172:173] op_sel_hi:[1,0]
	v_cvt_pk_bf16_f32 v83, v84, v85
	v_mad_i64_i32 v[84:85], s[12:13], v160, s96, v[112:113]
	v_lshl_add_u64 v[84:85], v[84:85], 0, v[114:115]
	global_store_dwordx4 v[84:85], v[80:83], off
	v_pk_mul_f32 v[68:69], v[68:69], v[172:173] op_sel_hi:[1,0]
	v_pk_mul_f32 v[72:73], v[72:73], v[172:173] op_sel_hi:[1,0]
	v_pk_mul_f32 v[80:81], v[66:67], v[172:173] op_sel_hi:[1,0]
	v_mul_f32_e32 v66, 0xbfb8aa3b, v76
	v_exp_f32_e32 v82, v66
	v_mul_f32_e32 v66, 0xbfb8aa3b, v77
	v_exp_f32_e32 v83, v66
	v_pk_mul_f32 v[66:67], v[64:65], v[172:173] op_sel_hi:[1,0]
	v_add_f32_e32 v64, 1.0, v82
	v_mul_f32_e32 v82, 0xbfb8aa3b, v78
	v_add_f32_e32 v65, 1.0, v83
	v_mul_f32_e32 v83, 0xbfb8aa3b, v79
	v_exp_f32_e32 v82, v82
	v_exp_f32_e32 v83, v83
	v_rcp_f32_e32 v64, v64
	v_rcp_f32_e32 v65, v65
	v_add_f32_e32 v82, 1.0, v82
	v_add_f32_e32 v83, 1.0, v83
	v_rcp_f32_e32 v82, v82
	v_rcp_f32_e32 v83, v83
	v_pk_mul_f32 v[64:65], v[76:77], v[64:65]
	v_pk_mul_f32 v[70:71], v[70:71], v[172:173] op_sel_hi:[1,0]
	v_pk_mul_f32 v[64:65], v[68:69], v[64:65]
	v_pk_mul_f32 v[68:69], v[78:79], v[82:83]
	v_cvt_pk_bf16_f32 v64, v64, v65
	v_mul_f32_e32 v65, 0xbfb8aa3b, v72
	v_pk_mul_f32 v[68:69], v[70:71], v[68:69]
	v_exp_f32_e32 v70, v65
	v_mul_f32_e32 v65, 0xbfb8aa3b, v73
	v_exp_f32_e32 v71, v65
	v_pk_mul_f32 v[74:75], v[74:75], v[172:173] op_sel_hi:[1,0]
	v_cvt_pk_bf16_f32 v65, v68, v69
	v_add_f32_e32 v68, 1.0, v70
	v_add_f32_e32 v69, 1.0, v71
	v_mul_f32_e32 v70, 0xbfb8aa3b, v74
	v_mul_f32_e32 v71, 0xbfb8aa3b, v75
	v_exp_f32_e32 v70, v70
	v_exp_f32_e32 v71, v71
	v_rcp_f32_e32 v68, v68
	v_rcp_f32_e32 v69, v69
	v_add_f32_e32 v70, 1.0, v70
	v_add_f32_e32 v71, 1.0, v71
	v_rcp_f32_e32 v70, v70
	v_rcp_f32_e32 v71, v71
	v_pk_mul_f32 v[68:69], v[72:73], v[68:69]
	ds_write_b32 v251, v166 offset:16
	v_pk_mul_f32 v[60:61], v[60:61], v[166:167] op_sel_hi:[1,0]
	v_pk_mul_f32 v[66:67], v[66:67], v[68:69]
	v_pk_mul_f32 v[68:69], v[74:75], v[70:71]
	v_cvt_pk_bf16_f32 v66, v66, v67
	v_pk_mul_f32 v[68:69], v[80:81], v[68:69]
	v_pk_mul_f32 v[62:63], v[62:63], v[166:167] op_sel_hi:[1,0]
	v_cvt_pk_bf16_f32 v67, v68, v69
	v_mad_i64_i32 v[68:69], s[12:13], v156, s96, v[112:113]
	v_lshl_add_u64 v[68:69], v[68:69], 0, v[114:115]
	global_store_dwordx4 v[68:69], v[64:67], off
	v_pk_mul_f32 v[52:53], v[52:53], v[166:167] op_sel_hi:[1,0]
	v_pk_mul_f32 v[56:57], v[56:57], v[166:167] op_sel_hi:[1,0]
	v_pk_mul_f32 v[64:65], v[50:51], v[166:167] op_sel_hi:[1,0]
	v_mul_f32_e32 v50, 0xbfb8aa3b, v60
	v_exp_f32_e32 v66, v50
	v_mul_f32_e32 v50, 0xbfb8aa3b, v61
	v_exp_f32_e32 v67, v50
	v_pk_mul_f32 v[50:51], v[48:49], v[166:167] op_sel_hi:[1,0]
	v_add_f32_e32 v48, 1.0, v66
	v_mul_f32_e32 v66, 0xbfb8aa3b, v62
	v_add_f32_e32 v49, 1.0, v67
	v_mul_f32_e32 v67, 0xbfb8aa3b, v63
	v_exp_f32_e32 v66, v66
	v_exp_f32_e32 v67, v67
	v_rcp_f32_e32 v48, v48
; __device__ __forceinline__ unsigned cvt_pk_bf16(float lo, float hi) { f32x2 v = {lo, hi}; bf16x2_t b = __builtin_convertvector(v, bf16x2_t); return __builtin_bit_cast(unsigned, b); }
; __device__ __forceinline__ float silu_f(float x) { return x * __builtin_amdgcn_rcpf(1.0f + __builtin_amdgcn_exp2f(-x * LOG2E)); }
;     __device__ __forceinline__ void operator()(const f32x4 (&acc)[2][2][4][2], const Unit& u, int wr, int wc, int fr, int fq) const {
;     ...
;             for (int m = 0; m < 4; ++m) { const int row = row0 + ai * HALF + m * 16; const float r = rs[ai][m];
;                 const f32x4 g0 = acc[ai][0][m][0] * r, g1 = acc[ai][0][m][1] * r, u0 = acc[ai][1][m][0] * r, u1 = acc[ai][1][m][1] * r;
;                 u32x4 w;
;                 w.x = cvt_pk_bf16(silu_f(g0[0]) * u0[0], silu_f(g0[1]) * u0[1]); w.y = cvt_pk_bf16(silu_f(g0[2]) * u0[2], silu_f(g0[3]) * u0[3]);
;                 w.z = cvt_pk_bf16(silu_f(g1[0]) * u1[0], silu_f(g1[1]) * u1[1]); w.w = cvt_pk_bf16(silu_f(g1[2]) * u1[2], silu_f(g1[3]) * u1[3]);
;                 *(u32x4*)(O + (size_t)row * ldo + col0) = w; }
	v_rcp_f32_e32 v49, v49
	v_add_f32_e32 v66, 1.0, v66
	v_add_f32_e32 v67, 1.0, v67
	v_rcp_f32_e32 v66, v66
	v_rcp_f32_e32 v67, v67
	v_pk_mul_f32 v[48:49], v[60:61], v[48:49]
	v_pk_mul_f32 v[54:55], v[54:55], v[166:167] op_sel_hi:[1,0]
	v_pk_mul_f32 v[48:49], v[52:53], v[48:49]
	v_pk_mul_f32 v[52:53], v[62:63], v[66:67]
	v_cvt_pk_bf16_f32 v48, v48, v49
	v_mul_f32_e32 v49, 0xbfb8aa3b, v56
	v_pk_mul_f32 v[52:53], v[54:55], v[52:53]
	v_exp_f32_e32 v54, v49
	v_mul_f32_e32 v49, 0xbfb8aa3b, v57
	v_exp_f32_e32 v55, v49
	v_pk_mul_f32 v[58:59], v[58:59], v[166:167] op_sel_hi:[1,0]
	v_cvt_pk_bf16_f32 v49, v52, v53
	v_add_f32_e32 v52, 1.0, v54
	v_add_f32_e32 v53, 1.0, v55
	v_mul_f32_e32 v54, 0xbfb8aa3b, v58
	v_mul_f32_e32 v55, 0xbfb8aa3b, v59
	v_exp_f32_e32 v54, v54
	v_exp_f32_e32 v55, v55
	v_rcp_f32_e32 v52, v52
	v_rcp_f32_e32 v53, v53
	v_add_f32_e32 v54, 1.0, v54
	v_add_f32_e32 v55, 1.0, v55
	v_rcp_f32_e32 v54, v54
	v_rcp_f32_e32 v55, v55
	v_pk_mul_f32 v[52:53], v[56:57], v[52:53]
	ds_write_b32 v251, v162 offset:20
	v_pk_mul_f32 v[44:45], v[44:45], v[162:163] op_sel_hi:[1,0]
	v_pk_mul_f32 v[50:51], v[50:51], v[52:53]
	v_pk_mul_f32 v[52:53], v[58:59], v[54:55]
	v_cvt_pk_bf16_f32 v50, v50, v51
	v_pk_mul_f32 v[52:53], v[64:65], v[52:53]
	v_pk_mul_f32 v[46:47], v[46:47], v[162:163] op_sel_hi:[1,0]
	v_cvt_pk_bf16_f32 v51, v52, v53
	v_mad_i64_i32 v[52:53], s[12:13], v152, s96, v[112:113]
	v_lshl_add_u64 v[52:53], v[52:53], 0, v[114:115]
	global_store_dwordx4 v[52:53], v[48:51], off
	v_pk_mul_f32 v[36:37], v[36:37], v[162:163] op_sel_hi:[1,0]
	v_pk_mul_f32 v[40:41], v[40:41], v[162:163] op_sel_hi:[1,0]
	v_pk_mul_f32 v[48:49], v[34:35], v[162:163] op_sel_hi:[1,0]
	v_mul_f32_e32 v34, 0xbfb8aa3b, v44
	v_exp_f32_e32 v50, v34
	v_mul_f32_e32 v34, 0xbfb8aa3b, v45
	v_exp_f32_e32 v51, v34
	v_pk_mul_f32 v[34:35], v[32:33], v[162:163] op_sel_hi:[1,0]
	v_add_f32_e32 v32, 1.0, v50
	v_mul_f32_e32 v50, 0xbfb8aa3b, v46
	v_add_f32_e32 v33, 1.0, v51
	v_mul_f32_e32 v51, 0xbfb8aa3b, v47
	v_exp_f32_e32 v50, v50
	v_exp_f32_e32 v51, v51
	v_rcp_f32_e32 v32, v32
	v_rcp_f32_e32 v33, v33
	v_add_f32_e32 v50, 1.0, v50
	v_add_f32_e32 v51, 1.0, v51
	v_rcp_f32_e32 v50, v50
	v_rcp_f32_e32 v51, v51
	v_pk_mul_f32 v[32:33], v[44:45], v[32:33]
	v_pk_mul_f32 v[38:39], v[38:39], v[162:163] op_sel_hi:[1,0]
	v_pk_mul_f32 v[32:33], v[36:37], v[32:33]
	v_pk_mul_f32 v[36:37], v[46:47], v[50:51]
	v_cvt_pk_bf16_f32 v32, v32, v33
	v_mul_f32_e32 v33, 0xbfb8aa3b, v40
	v_pk_mul_f32 v[36:37], v[38:39], v[36:37]
	v_exp_f32_e32 v38, v33
	v_mul_f32_e32 v33, 0xbfb8aa3b, v41
	v_exp_f32_e32 v39, v33
	v_pk_mul_f32 v[42:43], v[42:43], v[162:163] op_sel_hi:[1,0]
	v_cvt_pk_bf16_f32 v33, v36, v37
	v_add_f32_e32 v36, 1.0, v38
	v_add_f32_e32 v37, 1.0, v39
	v_mul_f32_e32 v38, 0xbfb8aa3b, v42
	v_mul_f32_e32 v39, 0xbfb8aa3b, v43
	v_exp_f32_e32 v38, v38
	v_exp_f32_e32 v39, v39
	v_rcp_f32_e32 v36, v36
	v_rcp_f32_e32 v37, v37
	v_add_f32_e32 v38, 1.0, v38
	v_add_f32_e32 v39, 1.0, v39
	v_rcp_f32_e32 v38, v38
	v_rcp_f32_e32 v39, v39
	v_pk_mul_f32 v[36:37], v[40:41], v[36:37]
	ds_write_b32 v251, v158 offset:28
	v_pk_mul_f32 v[28:29], v[28:29], v[158:159] op_sel_hi:[1,0]
	v_pk_mul_f32 v[34:35], v[34:35], v[36:37]
	v_pk_mul_f32 v[36:37], v[42:43], v[38:39]
	v_cvt_pk_bf16_f32 v34, v34, v35
	v_pk_mul_f32 v[36:37], v[48:49], v[36:37]
	v_pk_mul_f32 v[30:31], v[30:31], v[158:159] op_sel_hi:[1,0]
	v_cvt_pk_bf16_f32 v35, v36, v37
	v_mad_i64_i32 v[36:37], s[12:13], v150, s96, v[112:113]
	v_lshl_add_u64 v[36:37], v[36:37], 0, v[114:115]
	global_store_dwordx4 v[36:37], v[32:35], off
	v_pk_mul_f32 v[20:21], v[20:21], v[158:159] op_sel_hi:[1,0]
	v_pk_mul_f32 v[24:25], v[24:25], v[158:159] op_sel_hi:[1,0]
	v_pk_mul_f32 v[32:33], v[18:19], v[158:159] op_sel_hi:[1,0]
	v_mul_f32_e32 v18, 0xbfb8aa3b, v28
	v_exp_f32_e32 v34, v18
	v_mul_f32_e32 v18, 0xbfb8aa3b, v29
	v_exp_f32_e32 v35, v18
	v_pk_mul_f32 v[18:19], v[16:17], v[158:159] op_sel_hi:[1,0]
	v_add_f32_e32 v16, 1.0, v34
	v_mul_f32_e32 v34, 0xbfb8aa3b, v30
	v_add_f32_e32 v17, 1.0, v35
	v_mul_f32_e32 v35, 0xbfb8aa3b, v31
	v_exp_f32_e32 v34, v34
	v_exp_f32_e32 v35, v35
	v_rcp_f32_e32 v16, v16
	v_rcp_f32_e32 v17, v17
	v_add_f32_e32 v34, 1.0, v34
	v_add_f32_e32 v35, 1.0, v35
	v_rcp_f32_e32 v34, v34
	v_rcp_f32_e32 v35, v35
	v_pk_mul_f32 v[16:17], v[28:29], v[16:17]
	v_pk_mul_f32 v[22:23], v[22:23], v[158:159] op_sel_hi:[1,0]
	v_pk_mul_f32 v[16:17], v[20:21], v[16:17]
	v_pk_mul_f32 v[20:21], v[30:31], v[34:35]
	v_cvt_pk_bf16_f32 v16, v16, v17
	v_mul_f32_e32 v17, 0xbfb8aa3b, v24
	v_pk_mul_f32 v[20:21], v[22:23], v[20:21]
	v_exp_f32_e32 v22, v17
	v_mul_f32_e32 v17, 0xbfb8aa3b, v25
	v_exp_f32_e32 v23, v17
	v_pk_mul_f32 v[26:27], v[26:27], v[158:159] op_sel_hi:[1,0]
	v_cvt_pk_bf16_f32 v17, v20, v21
	v_add_f32_e32 v20, 1.0, v22
	v_add_f32_e32 v21, 1.0, v23
	v_mul_f32_e32 v22, 0xbfb8aa3b, v26
	v_mul_f32_e32 v23, 0xbfb8aa3b, v27
	v_exp_f32_e32 v22, v22
	v_exp_f32_e32 v23, v23
	v_rcp_f32_e32 v20, v20
	v_rcp_f32_e32 v21, v21
	v_add_f32_e32 v22, 1.0, v22
	v_add_f32_e32 v23, 1.0, v23
	v_rcp_f32_e32 v22, v22
	v_rcp_f32_e32 v23, v23
	v_pk_mul_f32 v[20:21], v[24:25], v[20:21]
	ds_write_b32 v251, v154 offset:24
	v_pk_mul_f32 v[12:13], v[12:13], v[154:155] op_sel_hi:[1,0]
	s_mov_b32 s100, 1
	s_branch .Lrc1_join
; __device__ __forceinline__ unsigned cvt_pk_bf16(float lo, float hi) { f32x2 v = {lo, hi}; bf16x2_t b = __builtin_convertvector(v, bf16x2_t); return __builtin_bit_cast(unsigned, b); }
; __device__ __forceinline__ float silu_f(float x) { return x * __builtin_amdgcn_rcpf(1.0f + __builtin_amdgcn_exp2f(-x * LOG2E)); }
;     __device__ __forceinline__ void operator()(const f32x4 (&acc)[2][2][4][2], const Unit& u, int wr, int wc, int fr, int fq) const {
;         const int row0 = u.pm * BM + wr * 64 + fr, col0 = u.pn * HALF + wc * 32 + 8 * fq;
;         float rs[2][4];
;         rows_rstd(ssq, row0, fq, 1.0f, rs);
; #pragma unroll
;         for (int ai = 0; ai < 2; ++ai)
; #pragma unroll
;             for (int m = 0; m < 4; ++m) { const int row = row0 + ai * HALF + m * 16; const float r = rs[ai][m];
;                 const f32x4 g0 = acc[ai][0][m][0] * r, g1 = acc[ai][0][m][1] * r, u0 = acc[ai][1][m][0] * r, u1 = acc[ai][1][m][1] * r;
;                 u32x4 w;
;                 w.x = cvt_pk_bf16(silu_f(g0[0]) * u0[0], silu_f(g0[1]) * u0[1]); w.y = cvt_pk_bf16(silu_f(g0[2]) * u0[2], silu_f(g0[3]) * u0[3]);
;                 w.z = cvt_pk_bf16(silu_f(g1[0]) * u1[0], silu_f(g1[1]) * u1[1]); w.w = cvt_pk_bf16(silu_f(g1[2]) * u1[2], silu_f(g1[3]) * u1[3]);
;                 *(u32x4*)(O + (size_t)row * ldo + col0) = w; }
.Lrc1_fast:
	v_lshrrev_b32_e32 v251, 6, v222
	v_and_b32_e32 v250, 15, v222
	v_lshl_or_b32 v251, v251, 4, v250
	v_lshlrev_b32_e32 v251, 5, v251
	v_add_u32_e32 v251, 0x20000, v251
	ds_read_b32 v169, v251
	ds_read_b32 v179, v251 offset:4
	ds_read_b32 v184, v251 offset:8
	ds_read_b32 v185, v251 offset:12
	ds_read_b32 v165, v251 offset:16
	ds_read_b32 v161, v251 offset:20
	ds_read_b32 v186, v251 offset:24
	ds_read_b32 v187, v251 offset:28
	s_waitcnt lgkmcnt(0)
	v_lshl_add_u32 v168, s88, 8, v155
	v_or_b32_e32 v164, 16, v168
	v_or_b32_e32 v160, 32, v168
	v_or_b32_e32 v156, 48, v168
	v_add_u32_e32 v152, 0x80, v168
	v_add_u32_e32 v150, 0x90, v168
	v_add_u32_e32 v148, 0xa0, v168
	v_add_u32_e32 v146, 0xb0, v168
	s_nop 0
	s_nop 0
	s_nop 0
	v_lshl_or_b32 v170, s97, 7, v163
	v_ashrrev_i32_e32 v171, 31, v170
	s_waitcnt lgkmcnt(0)
	s_waitcnt lgkmcnt(2)
	s_waitcnt lgkmcnt(1)
	s_waitcnt lgkmcnt(1)
	s_waitcnt lgkmcnt(2)
	s_waitcnt lgkmcnt(1)
	s_waitcnt lgkmcnt(0)
	s_waitcnt lgkmcnt(1)
	s_waitcnt lgkmcnt(0)
	s_waitcnt lgkmcnt(1)
	s_waitcnt lgkmcnt(0)
	v_mov_b32_e32 v180, v169
	v_pk_mul_f32 v[124:125], v[124:125], v[180:181] op_sel_hi:[1,0]
	v_pk_mul_f32 v[126:127], v[126:127], v[180:181] op_sel_hi:[1,0]
	s_waitcnt lgkmcnt(2)
	s_waitcnt lgkmcnt(1)
	s_waitcnt lgkmcnt(0)
	v_pk_mul_f32 v[122:123], v[122:123], v[180:181] op_sel_hi:[1,0]
	s_waitcnt lgkmcnt(1)
	s_waitcnt lgkmcnt(0)
	v_mul_f32_e32 v147, 0xbfb8aa3b, v124
	v_exp_f32_e32 v147, v147
	v_mul_f32_e32 v149, 0xbfb8aa3b, v125
	v_exp_f32_e32 v149, v149
	v_add_f32_e32 v147, 1.0, v147
	v_pk_mul_f32 v[120:121], v[120:121], v[180:181] op_sel_hi:[1,0]
	v_pk_mul_f32 v[118:119], v[118:119], v[180:181] op_sel_hi:[1,0]
	v_pk_mul_f32 v[116:117], v[116:117], v[180:181] op_sel_hi:[1,0]
	v_pk_mul_f32 v[114:115], v[114:115], v[180:181] op_sel_hi:[1,0]
	v_pk_mul_f32 v[112:113], v[112:113], v[180:181] op_sel_hi:[1,0]
	v_rcp_f32_e32 v180, v147
	v_add_f32_e32 v147, 1.0, v149
	v_mul_f32_e32 v149, 0xbfb8aa3b, v126
	v_exp_f32_e32 v149, v149
	v_mul_f32_e32 v151, 0xbfb8aa3b, v127
	v_exp_f32_e32 v151, v151
	v_rcp_f32_e32 v181, v147
	v_add_f32_e32 v147, 1.0, v149
	v_rcp_f32_e32 v182, v147
	v_add_f32_e32 v147, 1.0, v151
	v_rcp_f32_e32 v183, v147
	v_pk_mul_f32 v[124:125], v[124:125], v[180:181]
	v_mov_b32_e32 v178, v179
	v_pk_mul_f32 v[108:109], v[108:109], v[178:179] op_sel_hi:[1,0]
	v_pk_mul_f32 v[116:117], v[116:117], v[124:125]
	v_pk_mul_f32 v[124:125], v[126:127], v[182:183]
	v_cvt_pk_bf16_f32 v116, v116, v117
	v_mul_f32_e32 v117, 0xbfb8aa3b, v120
	v_pk_mul_f32 v[118:119], v[118:119], v[124:125]
	v_exp_f32_e32 v124, v117
	v_mul_f32_e32 v117, 0xbfb8aa3b, v121
	v_exp_f32_e32 v125, v117
	v_cvt_pk_bf16_f32 v117, v118, v119
	v_add_f32_e32 v118, 1.0, v124
	v_mul_f32_e32 v124, 0xbfb8aa3b, v122
	v_add_f32_e32 v119, 1.0, v125
	v_mul_f32_e32 v125, 0xbfb8aa3b, v123
	v_exp_f32_e32 v124, v124
	v_exp_f32_e32 v125, v125
	v_rcp_f32_e32 v118, v118
	v_rcp_f32_e32 v119, v119
	v_add_f32_e32 v124, 1.0, v124
	v_add_f32_e32 v125, 1.0, v125
	v_rcp_f32_e32 v124, v124
	v_rcp_f32_e32 v125, v125
	v_pk_mul_f32 v[118:119], v[120:121], v[118:119]
	v_pk_mul_f32 v[110:111], v[110:111], v[178:179] op_sel_hi:[1,0]
	v_pk_mul_f32 v[112:113], v[112:113], v[118:119]
	v_pk_mul_f32 v[100:101], v[100:101], v[178:179] op_sel_hi:[1,0]
	v_cvt_pk_bf16_f32 v118, v112, v113
	v_pk_mul_f32 v[112:113], v[122:123], v[124:125]
	v_pk_mul_f32 v[104:105], v[104:105], v[178:179] op_sel_hi:[1,0]
	v_pk_mul_f32 v[112:113], v[114:115], v[112:113]
	v_lshlrev_b64 v[114:115], 1, v[170:171]
	v_cvt_pk_bf16_f32 v119, v112, v113
	v_mov_b64_e32 v[112:113], s[38:39]
	v_mad_i64_i32 v[120:121], s[12:13], v168, s96, v[112:113]
	v_lshl_add_u64 v[120:121], v[120:121], 0, v[114:115]
	global_store_dwordx4 v[120:121], v[116:119], off
	v_pk_mul_f32 v[102:103], v[102:103], v[178:179] op_sel_hi:[1,0]
	v_pk_mul_f32 v[106:107], v[106:107], v[178:179] op_sel_hi:[1,0]
	v_pk_mul_f32 v[116:117], v[98:99], v[178:179] op_sel_hi:[1,0]
	v_mul_f32_e32 v98, 0xbfb8aa3b, v108
	v_exp_f32_e32 v118, v98
	v_mul_f32_e32 v98, 0xbfb8aa3b, v109
	v_exp_f32_e32 v119, v98
	v_pk_mul_f32 v[98:99], v[96:97], v[178:179] op_sel_hi:[1,0]
	v_add_f32_e32 v96, 1.0, v118
	v_mul_f32_e32 v118, 0xbfb8aa3b, v110
	v_add_f32_e32 v97, 1.0, v119
	v_mul_f32_e32 v119, 0xbfb8aa3b, v111
	v_exp_f32_e32 v118, v118
	v_exp_f32_e32 v119, v119
	v_rcp_f32_e32 v96, v96
	v_rcp_f32_e32 v97, v97
	v_add_f32_e32 v118, 1.0, v118
	v_add_f32_e32 v119, 1.0, v119
	v_rcp_f32_e32 v118, v118
	v_rcp_f32_e32 v119, v119
	v_pk_mul_f32 v[96:97], v[108:109], v[96:97]
	v_mov_b32_e32 v174, v184
	v_pk_mul_f32 v[92:93], v[92:93], v[174:175] op_sel_hi:[1,0]
	v_pk_mul_f32 v[96:97], v[100:101], v[96:97]
	v_pk_mul_f32 v[100:101], v[110:111], v[118:119]
	v_cvt_pk_bf16_f32 v96, v96, v97
	v_mul_f32_e32 v97, 0xbfb8aa3b, v104
	v_pk_mul_f32 v[100:101], v[102:103], v[100:101]
	v_exp_f32_e32 v102, v97
	v_mul_f32_e32 v97, 0xbfb8aa3b, v105
	v_exp_f32_e32 v103, v97
	v_cvt_pk_bf16_f32 v97, v100, v101
	v_add_f32_e32 v100, 1.0, v102
	v_mul_f32_e32 v102, 0xbfb8aa3b, v106
	v_add_f32_e32 v101, 1.0, v103
	v_mul_f32_e32 v103, 0xbfb8aa3b, v107
	v_exp_f32_e32 v102, v102
	v_exp_f32_e32 v103, v103
	v_rcp_f32_e32 v100, v100
	v_rcp_f32_e32 v101, v101
	v_add_f32_e32 v102, 1.0, v102
	v_add_f32_e32 v103, 1.0, v103
	v_rcp_f32_e32 v102, v102
	v_rcp_f32_e32 v103, v103
	v_pk_mul_f32 v[100:101], v[104:105], v[100:101]
	v_pk_mul_f32 v[94:95], v[94:95], v[174:175] op_sel_hi:[1,0]
	v_pk_mul_f32 v[98:99], v[98:99], v[100:101]
	v_pk_mul_f32 v[100:101], v[106:107], v[102:103]
	v_cvt_pk_bf16_f32 v98, v98, v99
	v_pk_mul_f32 v[100:101], v[116:117], v[100:101]
	v_pk_mul_f32 v[84:85], v[84:85], v[174:175] op_sel_hi:[1,0]
; __device__ __forceinline__ unsigned cvt_pk_bf16(float lo, float hi) { f32x2 v = {lo, hi}; bf16x2_t b = __builtin_convertvector(v, bf16x2_t); return __builtin_bit_cast(unsigned, b); }
; __device__ __forceinline__ float silu_f(float x) { return x * __builtin_amdgcn_rcpf(1.0f + __builtin_amdgcn_exp2f(-x * LOG2E)); }
;     __device__ __forceinline__ void operator()(const f32x4 (&acc)[2][2][4][2], const Unit& u, int wr, int wc, int fr, int fq) const {
;     ...
;             for (int m = 0; m < 4; ++m) { const int row = row0 + ai * HALF + m * 16; const float r = rs[ai][m];
;                 const f32x4 g0 = acc[ai][0][m][0] * r, g1 = acc[ai][0][m][1] * r, u0 = acc[ai][1][m][0] * r, u1 = acc[ai][1][m][1] * r;
;                 u32x4 w;
;                 w.x = cvt_pk_bf16(silu_f(g0[0]) * u0[0], silu_f(g0[1]) * u0[1]); w.y = cvt_pk_bf16(silu_f(g0[2]) * u0[2], silu_f(g0[3]) * u0[3]);
;                 w.z = cvt_pk_bf16(silu_f(g1[0]) * u1[0], silu_f(g1[1]) * u1[1]); w.w = cvt_pk_bf16(silu_f(g1[2]) * u1[2], silu_f(g1[3]) * u1[3]);
;                 *(u32x4*)(O + (size_t)row * ldo + col0) = w; }
	v_cvt_pk_bf16_f32 v99, v100, v101
	v_mad_i64_i32 v[100:101], s[12:13], v164, s96, v[112:113]
	v_lshl_add_u64 v[100:101], v[100:101], 0, v[114:115]
	global_store_dwordx4 v[100:101], v[96:99], off
	v_pk_mul_f32 v[88:89], v[88:89], v[174:175] op_sel_hi:[1,0]
	v_pk_mul_f32 v[86:87], v[86:87], v[174:175] op_sel_hi:[1,0]
	v_pk_mul_f32 v[96:97], v[82:83], v[174:175] op_sel_hi:[1,0]
	v_mul_f32_e32 v82, 0xbfb8aa3b, v92
	v_exp_f32_e32 v98, v82
	v_mul_f32_e32 v82, 0xbfb8aa3b, v93
	v_exp_f32_e32 v99, v82
	v_pk_mul_f32 v[82:83], v[80:81], v[174:175] op_sel_hi:[1,0]
	v_add_f32_e32 v80, 1.0, v98
	v_mul_f32_e32 v98, 0xbfb8aa3b, v94
	v_add_f32_e32 v81, 1.0, v99
	v_mul_f32_e32 v99, 0xbfb8aa3b, v95
	v_exp_f32_e32 v98, v98
	v_exp_f32_e32 v99, v99
	v_rcp_f32_e32 v80, v80
	v_rcp_f32_e32 v81, v81
	v_add_f32_e32 v98, 1.0, v98
	v_add_f32_e32 v99, 1.0, v99
	v_rcp_f32_e32 v98, v98
	v_rcp_f32_e32 v99, v99
	v_pk_mul_f32 v[80:81], v[92:93], v[80:81]
	v_pk_mul_f32 v[90:91], v[90:91], v[174:175] op_sel_hi:[1,0]
	v_pk_mul_f32 v[80:81], v[84:85], v[80:81]
	v_pk_mul_f32 v[84:85], v[94:95], v[98:99]
	v_cvt_pk_bf16_f32 v80, v80, v81
	v_mul_f32_e32 v81, 0xbfb8aa3b, v88
	v_pk_mul_f32 v[84:85], v[86:87], v[84:85]
	v_exp_f32_e32 v86, v81
	v_mul_f32_e32 v81, 0xbfb8aa3b, v89
	v_exp_f32_e32 v87, v81
	v_cvt_pk_bf16_f32 v81, v84, v85
	v_add_f32_e32 v84, 1.0, v86
	v_mul_f32_e32 v86, 0xbfb8aa3b, v90
	v_add_f32_e32 v85, 1.0, v87
	v_mul_f32_e32 v87, 0xbfb8aa3b, v91
	v_exp_f32_e32 v86, v86
	v_exp_f32_e32 v87, v87
	v_rcp_f32_e32 v84, v84
	v_rcp_f32_e32 v85, v85
	v_add_f32_e32 v86, 1.0, v86
	v_add_f32_e32 v87, 1.0, v87
	v_rcp_f32_e32 v86, v86
	v_rcp_f32_e32 v87, v87
	v_pk_mul_f32 v[84:85], v[88:89], v[84:85]
	v_mov_b32_e32 v172, v185
	v_pk_mul_f32 v[76:77], v[76:77], v[172:173] op_sel_hi:[1,0]
	v_pk_mul_f32 v[82:83], v[82:83], v[84:85]
	v_pk_mul_f32 v[84:85], v[90:91], v[86:87]
	v_cvt_pk_bf16_f32 v82, v82, v83
	v_pk_mul_f32 v[84:85], v[96:97], v[84:85]
	v_pk_mul_f32 v[78:79], v[78:79], v[172:173] op_sel_hi:[1,0]
	v_cvt_pk_bf16_f32 v83, v84, v85
	v_mad_i64_i32 v[84:85], s[12:13], v160, s96, v[112:113]
	v_lshl_add_u64 v[84:85], v[84:85], 0, v[114:115]
	global_store_dwordx4 v[84:85], v[80:83], off
	v_pk_mul_f32 v[68:69], v[68:69], v[172:173] op_sel_hi:[1,0]
	v_pk_mul_f32 v[72:73], v[72:73], v[172:173] op_sel_hi:[1,0]
	v_pk_mul_f32 v[80:81], v[66:67], v[172:173] op_sel_hi:[1,0]
	v_mul_f32_e32 v66, 0xbfb8aa3b, v76
	v_exp_f32_e32 v82, v66
	v_mul_f32_e32 v66, 0xbfb8aa3b, v77
	v_exp_f32_e32 v83, v66
	v_pk_mul_f32 v[66:67], v[64:65], v[172:173] op_sel_hi:[1,0]
	v_add_f32_e32 v64, 1.0, v82
	v_mul_f32_e32 v82, 0xbfb8aa3b, v78
	v_add_f32_e32 v65, 1.0, v83
	v_mul_f32_e32 v83, 0xbfb8aa3b, v79
	v_exp_f32_e32 v82, v82
	v_exp_f32_e32 v83, v83
	v_rcp_f32_e32 v64, v64
	v_rcp_f32_e32 v65, v65
	v_add_f32_e32 v82, 1.0, v82
	v_add_f32_e32 v83, 1.0, v83
	v_rcp_f32_e32 v82, v82
	v_rcp_f32_e32 v83, v83
	v_pk_mul_f32 v[64:65], v[76:77], v[64:65]
	v_pk_mul_f32 v[70:71], v[70:71], v[172:173] op_sel_hi:[1,0]
	v_pk_mul_f32 v[64:65], v[68:69], v[64:65]
	v_pk_mul_f32 v[68:69], v[78:79], v[82:83]
	v_cvt_pk_bf16_f32 v64, v64, v65
	v_mul_f32_e32 v65, 0xbfb8aa3b, v72
	v_pk_mul_f32 v[68:69], v[70:71], v[68:69]
	v_exp_f32_e32 v70, v65
	v_mul_f32_e32 v65, 0xbfb8aa3b, v73
	v_exp_f32_e32 v71, v65
	v_pk_mul_f32 v[74:75], v[74:75], v[172:173] op_sel_hi:[1,0]
	v_cvt_pk_bf16_f32 v65, v68, v69
	v_add_f32_e32 v68, 1.0, v70
	v_add_f32_e32 v69, 1.0, v71
	v_mul_f32_e32 v70, 0xbfb8aa3b, v74
	v_mul_f32_e32 v71, 0xbfb8aa3b, v75
	v_exp_f32_e32 v70, v70
	v_exp_f32_e32 v71, v71
	v_rcp_f32_e32 v68, v68
	v_rcp_f32_e32 v69, v69
	v_add_f32_e32 v70, 1.0, v70
	v_add_f32_e32 v71, 1.0, v71
	v_rcp_f32_e32 v70, v70
	v_rcp_f32_e32 v71, v71
	v_pk_mul_f32 v[68:69], v[72:73], v[68:69]
	v_mov_b32_e32 v166, v165
	v_pk_mul_f32 v[60:61], v[60:61], v[166:167] op_sel_hi:[1,0]
	v_pk_mul_f32 v[66:67], v[66:67], v[68:69]
	v_pk_mul_f32 v[68:69], v[74:75], v[70:71]
	v_cvt_pk_bf16_f32 v66, v66, v67
	v_pk_mul_f32 v[68:69], v[80:81], v[68:69]
	v_pk_mul_f32 v[62:63], v[62:63], v[166:167] op_sel_hi:[1,0]
	v_cvt_pk_bf16_f32 v67, v68, v69
	v_mad_i64_i32 v[68:69], s[12:13], v156, s96, v[112:113]
	v_lshl_add_u64 v[68:69], v[68:69], 0, v[114:115]
	global_store_dwordx4 v[68:69], v[64:67], off
	v_pk_mul_f32 v[52:53], v[52:53], v[166:167] op_sel_hi:[1,0]
	v_pk_mul_f32 v[56:57], v[56:57], v[166:167] op_sel_hi:[1,0]
	v_pk_mul_f32 v[64:65], v[50:51], v[166:167] op_sel_hi:[1,0]
	v_mul_f32_e32 v50, 0xbfb8aa3b, v60
	v_exp_f32_e32 v66, v50
	v_mul_f32_e32 v50, 0xbfb8aa3b, v61
	v_exp_f32_e32 v67, v50
	v_pk_mul_f32 v[50:51], v[48:49], v[166:167] op_sel_hi:[1,0]
	v_add_f32_e32 v48, 1.0, v66
	v_mul_f32_e32 v66, 0xbfb8aa3b, v62
	v_add_f32_e32 v49, 1.0, v67
	v_mul_f32_e32 v67, 0xbfb8aa3b, v63
	v_exp_f32_e32 v66, v66
	v_exp_f32_e32 v67, v67
	v_rcp_f32_e32 v48, v48
	v_rcp_f32_e32 v49, v49
	v_add_f32_e32 v66, 1.0, v66
	v_add_f32_e32 v67, 1.0, v67
	v_rcp_f32_e32 v66, v66
	v_rcp_f32_e32 v67, v67
	v_pk_mul_f32 v[48:49], v[60:61], v[48:49]
	v_pk_mul_f32 v[54:55], v[54:55], v[166:167] op_sel_hi:[1,0]
	v_pk_mul_f32 v[48:49], v[52:53], v[48:49]
	v_pk_mul_f32 v[52:53], v[62:63], v[66:67]
	v_cvt_pk_bf16_f32 v48, v48, v49
	v_mul_f32_e32 v49, 0xbfb8aa3b, v56
	v_pk_mul_f32 v[52:53], v[54:55], v[52:53]
	v_exp_f32_e32 v54, v49
	v_mul_f32_e32 v49, 0xbfb8aa3b, v57
	v_exp_f32_e32 v55, v49
	v_pk_mul_f32 v[58:59], v[58:59], v[166:167] op_sel_hi:[1,0]
	v_cvt_pk_bf16_f32 v49, v52, v53
	v_add_f32_e32 v52, 1.0, v54
	v_add_f32_e32 v53, 1.0, v55
	v_mul_f32_e32 v54, 0xbfb8aa3b, v58
	v_mul_f32_e32 v55, 0xbfb8aa3b, v59
	v_exp_f32_e32 v54, v54
	v_exp_f32_e32 v55, v55
	v_rcp_f32_e32 v52, v52
	v_rcp_f32_e32 v53, v53
; __device__ __forceinline__ unsigned cvt_pk_bf16(float lo, float hi) { f32x2 v = {lo, hi}; bf16x2_t b = __builtin_convertvector(v, bf16x2_t); return __builtin_bit_cast(unsigned, b); }
; __device__ __forceinline__ float silu_f(float x) { return x * __builtin_amdgcn_rcpf(1.0f + __builtin_amdgcn_exp2f(-x * LOG2E)); }
; #define PG8_BAR __builtin_amdgcn_s_barrier()
;     __device__ __forceinline__ void operator()(const f32x4 (&acc)[2][2][4][2], const Unit& u, int wr, int wc, int fr, int fq) const {
;     ...
;             for (int m = 0; m < 4; ++m) { const int row = row0 + ai * HALF + m * 16; const float r = rs[ai][m];
;                 const f32x4 g0 = acc[ai][0][m][0] * r, g1 = acc[ai][0][m][1] * r, u0 = acc[ai][1][m][0] * r, u1 = acc[ai][1][m][1] * r;
;                 u32x4 w;
;                 w.x = cvt_pk_bf16(silu_f(g0[0]) * u0[0], silu_f(g0[1]) * u0[1]); w.y = cvt_pk_bf16(silu_f(g0[2]) * u0[2], silu_f(g0[3]) * u0[3]);
;                 w.z = cvt_pk_bf16(silu_f(g1[0]) * u1[0], silu_f(g1[1]) * u1[1]); w.w = cvt_pk_bf16(silu_f(g1[2]) * u1[2], silu_f(g1[3]) * u1[3]);
;                 *(u32x4*)(O + (size_t)row * ldo + col0) = w; }
; template <class Epi, class Sched, bool ALIGN_EPI = false, bool SP2 = false>
; __device__ __forceinline__ void gemm_phase(PG8_LAS unsigned char* lds, const Gemm g, const Sched& S, const Epi& E) {
;     ...
;         if constexpr (!Epi::AFTER_DRAIN) { E(acc, cur, wr, wc, fr, fq); S.done(cur); }
;         if (!has_next) break;
; #pragma unroll
;         for (int a = 0; a < 2; ++a)
; #pragma unroll
;             for (int b = 0; b < 2; ++b)
; #pragma unroll
;                 for (int m = 0; m < 4; ++m)
; #pragma unroll
;                     for (int n = 0; n < 2; ++n) acc[a][b][m][n] = (f32x4){0.f, 0.f, 0.f, 0.f};
;         cur = nxt; cA = nA; cB = nB; ++ui;
;         if constexpr (ALIGN_EPI) { if (wr == 1) PG8_BAR; }
	v_add_f32_e32 v54, 1.0, v54
	v_add_f32_e32 v55, 1.0, v55
	v_rcp_f32_e32 v54, v54
	v_rcp_f32_e32 v55, v55
	v_pk_mul_f32 v[52:53], v[56:57], v[52:53]
	v_mov_b32_e32 v162, v161
	v_pk_mul_f32 v[44:45], v[44:45], v[162:163] op_sel_hi:[1,0]
	v_pk_mul_f32 v[50:51], v[50:51], v[52:53]
	v_pk_mul_f32 v[52:53], v[58:59], v[54:55]
	v_cvt_pk_bf16_f32 v50, v50, v51
	v_pk_mul_f32 v[52:53], v[64:65], v[52:53]
	v_pk_mul_f32 v[46:47], v[46:47], v[162:163] op_sel_hi:[1,0]
	v_cvt_pk_bf16_f32 v51, v52, v53
	v_mad_i64_i32 v[52:53], s[12:13], v152, s96, v[112:113]
	v_lshl_add_u64 v[52:53], v[52:53], 0, v[114:115]
	global_store_dwordx4 v[52:53], v[48:51], off
	v_pk_mul_f32 v[36:37], v[36:37], v[162:163] op_sel_hi:[1,0]
	v_pk_mul_f32 v[40:41], v[40:41], v[162:163] op_sel_hi:[1,0]
	v_pk_mul_f32 v[48:49], v[34:35], v[162:163] op_sel_hi:[1,0]
	v_mul_f32_e32 v34, 0xbfb8aa3b, v44
	v_exp_f32_e32 v50, v34
	v_mul_f32_e32 v34, 0xbfb8aa3b, v45
	v_exp_f32_e32 v51, v34
	v_pk_mul_f32 v[34:35], v[32:33], v[162:163] op_sel_hi:[1,0]
	v_add_f32_e32 v32, 1.0, v50
	v_mul_f32_e32 v50, 0xbfb8aa3b, v46
	v_add_f32_e32 v33, 1.0, v51
	v_mul_f32_e32 v51, 0xbfb8aa3b, v47
	v_exp_f32_e32 v50, v50
	v_exp_f32_e32 v51, v51
	v_rcp_f32_e32 v32, v32
	v_rcp_f32_e32 v33, v33
	v_add_f32_e32 v50, 1.0, v50
	v_add_f32_e32 v51, 1.0, v51
	v_rcp_f32_e32 v50, v50
	v_rcp_f32_e32 v51, v51
	v_pk_mul_f32 v[32:33], v[44:45], v[32:33]
	v_pk_mul_f32 v[38:39], v[38:39], v[162:163] op_sel_hi:[1,0]
	v_pk_mul_f32 v[32:33], v[36:37], v[32:33]
	v_pk_mul_f32 v[36:37], v[46:47], v[50:51]
	v_cvt_pk_bf16_f32 v32, v32, v33
	v_mul_f32_e32 v33, 0xbfb8aa3b, v40
	v_pk_mul_f32 v[36:37], v[38:39], v[36:37]
	v_exp_f32_e32 v38, v33
	v_mul_f32_e32 v33, 0xbfb8aa3b, v41
	v_exp_f32_e32 v39, v33
	v_pk_mul_f32 v[42:43], v[42:43], v[162:163] op_sel_hi:[1,0]
	v_cvt_pk_bf16_f32 v33, v36, v37
	v_add_f32_e32 v36, 1.0, v38
	v_add_f32_e32 v37, 1.0, v39
	v_mul_f32_e32 v38, 0xbfb8aa3b, v42
	v_mul_f32_e32 v39, 0xbfb8aa3b, v43
	v_exp_f32_e32 v38, v38
	v_exp_f32_e32 v39, v39
	v_rcp_f32_e32 v36, v36
	v_rcp_f32_e32 v37, v37
	v_add_f32_e32 v38, 1.0, v38
	v_add_f32_e32 v39, 1.0, v39
	v_rcp_f32_e32 v38, v38
	v_rcp_f32_e32 v39, v39
	v_pk_mul_f32 v[36:37], v[40:41], v[36:37]
	v_mov_b32_e32 v158, v187
	v_pk_mul_f32 v[28:29], v[28:29], v[158:159] op_sel_hi:[1,0]
	v_pk_mul_f32 v[34:35], v[34:35], v[36:37]
	v_pk_mul_f32 v[36:37], v[42:43], v[38:39]
	v_cvt_pk_bf16_f32 v34, v34, v35
	v_pk_mul_f32 v[36:37], v[48:49], v[36:37]
	v_pk_mul_f32 v[30:31], v[30:31], v[158:159] op_sel_hi:[1,0]
	v_cvt_pk_bf16_f32 v35, v36, v37
	v_mad_i64_i32 v[36:37], s[12:13], v150, s96, v[112:113]
	v_lshl_add_u64 v[36:37], v[36:37], 0, v[114:115]
	global_store_dwordx4 v[36:37], v[32:35], off
	v_pk_mul_f32 v[20:21], v[20:21], v[158:159] op_sel_hi:[1,0]
	v_pk_mul_f32 v[24:25], v[24:25], v[158:159] op_sel_hi:[1,0]
	v_pk_mul_f32 v[32:33], v[18:19], v[158:159] op_sel_hi:[1,0]
	v_mul_f32_e32 v18, 0xbfb8aa3b, v28
	v_exp_f32_e32 v34, v18
	v_mul_f32_e32 v18, 0xbfb8aa3b, v29
	v_exp_f32_e32 v35, v18
	v_pk_mul_f32 v[18:19], v[16:17], v[158:159] op_sel_hi:[1,0]
	v_add_f32_e32 v16, 1.0, v34
	v_mul_f32_e32 v34, 0xbfb8aa3b, v30
	v_add_f32_e32 v17, 1.0, v35
	v_mul_f32_e32 v35, 0xbfb8aa3b, v31
	v_exp_f32_e32 v34, v34
	v_exp_f32_e32 v35, v35
	v_rcp_f32_e32 v16, v16
	v_rcp_f32_e32 v17, v17
	v_add_f32_e32 v34, 1.0, v34
	v_add_f32_e32 v35, 1.0, v35
	v_rcp_f32_e32 v34, v34
	v_rcp_f32_e32 v35, v35
	v_pk_mul_f32 v[16:17], v[28:29], v[16:17]
	v_pk_mul_f32 v[22:23], v[22:23], v[158:159] op_sel_hi:[1,0]
	v_pk_mul_f32 v[16:17], v[20:21], v[16:17]
	v_pk_mul_f32 v[20:21], v[30:31], v[34:35]
	v_cvt_pk_bf16_f32 v16, v16, v17
	v_mul_f32_e32 v17, 0xbfb8aa3b, v24
	v_pk_mul_f32 v[20:21], v[22:23], v[20:21]
	v_exp_f32_e32 v22, v17
	v_mul_f32_e32 v17, 0xbfb8aa3b, v25
	v_exp_f32_e32 v23, v17
	v_pk_mul_f32 v[26:27], v[26:27], v[158:159] op_sel_hi:[1,0]
	v_cvt_pk_bf16_f32 v17, v20, v21
	v_add_f32_e32 v20, 1.0, v22
	v_add_f32_e32 v21, 1.0, v23
	v_mul_f32_e32 v22, 0xbfb8aa3b, v26
	v_mul_f32_e32 v23, 0xbfb8aa3b, v27
	v_exp_f32_e32 v22, v22
	v_exp_f32_e32 v23, v23
	v_rcp_f32_e32 v20, v20
	v_rcp_f32_e32 v21, v21
	v_add_f32_e32 v22, 1.0, v22
	v_add_f32_e32 v23, 1.0, v23
	v_rcp_f32_e32 v22, v22
	v_rcp_f32_e32 v23, v23
	v_pk_mul_f32 v[20:21], v[24:25], v[20:21]
	v_mov_b32_e32 v154, v186
	v_pk_mul_f32 v[12:13], v[12:13], v[154:155] op_sel_hi:[1,0]
.Lrc1_join:
	v_pk_mul_f32 v[18:19], v[18:19], v[20:21]
	v_pk_mul_f32 v[20:21], v[26:27], v[22:23]
	v_cvt_pk_bf16_f32 v18, v18, v19
	v_pk_mul_f32 v[20:21], v[32:33], v[20:21]
	v_pk_mul_f32 v[14:15], v[14:15], v[154:155] op_sel_hi:[1,0]
	v_cvt_pk_bf16_f32 v19, v20, v21
	v_mad_i64_i32 v[20:21], s[12:13], v148, s96, v[112:113]
	v_lshl_add_u64 v[20:21], v[20:21], 0, v[114:115]
	global_store_dwordx4 v[20:21], v[16:19], off
	v_pk_mul_f32 v[4:5], v[4:5], v[154:155] op_sel_hi:[1,0]
	v_pk_mul_f32 v[8:9], v[8:9], v[154:155] op_sel_hi:[1,0]
	v_pk_mul_f32 v[16:17], v[2:3], v[154:155] op_sel_hi:[1,0]
	v_mul_f32_e32 v2, 0xbfb8aa3b, v12
	v_exp_f32_e32 v18, v2
	v_mul_f32_e32 v2, 0xbfb8aa3b, v13
	v_exp_f32_e32 v19, v2
	v_pk_mul_f32 v[2:3], v[0:1], v[154:155] op_sel_hi:[1,0]
	v_add_f32_e32 v0, 1.0, v18
	v_mul_f32_e32 v18, 0xbfb8aa3b, v14
	v_add_f32_e32 v1, 1.0, v19
	v_mul_f32_e32 v19, 0xbfb8aa3b, v15
	v_exp_f32_e32 v18, v18
	v_exp_f32_e32 v19, v19
	v_rcp_f32_e32 v0, v0
	v_rcp_f32_e32 v1, v1
	v_add_f32_e32 v18, 1.0, v18
	v_add_f32_e32 v19, 1.0, v19
	v_rcp_f32_e32 v18, v18
	v_rcp_f32_e32 v19, v19
	v_pk_mul_f32 v[0:1], v[12:13], v[0:1]
	v_pk_mul_f32 v[6:7], v[6:7], v[154:155] op_sel_hi:[1,0]
	v_pk_mul_f32 v[0:1], v[4:5], v[0:1]
	v_pk_mul_f32 v[4:5], v[14:15], v[18:19]
	v_cvt_pk_bf16_f32 v0, v0, v1
	v_mul_f32_e32 v1, 0xbfb8aa3b, v8
	v_pk_mul_f32 v[4:5], v[6:7], v[4:5]
	v_exp_f32_e32 v6, v1
	v_mul_f32_e32 v1, 0xbfb8aa3b, v9
	v_exp_f32_e32 v7, v1
	v_pk_mul_f32 v[10:11], v[10:11], v[154:155] op_sel_hi:[1,0]
	v_cvt_pk_bf16_f32 v1, v4, v5
	v_add_f32_e32 v4, 1.0, v6
	v_add_f32_e32 v5, 1.0, v7
	v_mul_f32_e32 v6, 0xbfb8aa3b, v10
	v_mul_f32_e32 v7, 0xbfb8aa3b, v11
	v_exp_f32_e32 v6, v6
	v_exp_f32_e32 v7, v7
	v_rcp_f32_e32 v4, v4
	v_rcp_f32_e32 v5, v5
	v_add_f32_e32 v6, 1.0, v6
	v_add_f32_e32 v7, 1.0, v7
	v_rcp_f32_e32 v6, v6
	v_rcp_f32_e32 v7, v7
	v_pk_mul_f32 v[4:5], v[8:9], v[4:5]
	s_andn2_b64 vcc, exec, s[4:5]
	v_pk_mul_f32 v[2:3], v[2:3], v[4:5]
	v_pk_mul_f32 v[4:5], v[10:11], v[6:7]
	v_cvt_pk_bf16_f32 v2, v2, v3
	v_pk_mul_f32 v[4:5], v[16:17], v[4:5]
	s_mov_b64 s[4:5], -1
	v_cvt_pk_bf16_f32 v3, v4, v5
	v_mad_i64_i32 v[4:5], s[12:13], v146, s96, v[112:113]
	v_lshl_add_u64 v[4:5], v[4:5], 0, v[114:115]
	global_store_dwordx4 v[4:5], v[0:3], off
	s_cbranch_vccnz .LBB0_123
	s_andn2_b64 vcc, exec, s[6:7]
	s_cbranch_vccnz .LBB0_122
	s_barrier
	s_branch .LBB0_122

; template <class Epi, class Sched, bool ALIGN_EPI = false, bool SP2 = false>
; __device__ __forceinline__ void gemm_phase(PG8_LAS unsigned char* lds, const Gemm g, const Sched& S, const Epi& E) {
;     ...
;     const int tid = tid_o, wid = __builtin_amdgcn_readfirstlane(tid >> 6), lane = tid & 63, wr = wid >> 2, wc = wid & 3, fr = lane & 15, fq = lane >> 4;
;     const int K = g.K, nt = K / BK;
;     unsigned voffA[2], voffB[2];
; #pragma unroll
;     for (int i = 0; i < 2; ++i) { int R, C; stage_rc(tid * 16 + i * 8192, R, C); const int Rb = Epi::PERM ? ((R & ~31) + perm32(R & 31)) : R;
;         voffA[i] = (unsigned)(R * K + C) * 2u; voffB[i] = (unsigned)(Rb * K + C) * 2u; }
;     const size_t kstep = (size_t)(BK * 2);
;     const size_t hstep = (size_t)HALF * K * 2;
;     const size_t tstep = 2 * hstep;
;     const unsigned ldsw = (unsigned)wid * 1024u;
;     const int aoff = lds_byte(wr * 64 + fr, fq * 8), boff = lds_byte(wc * 32 + fr, fq * 8);
;     ...
;     Unit cur, nxt; int ui = 0;
;     if (!S.next(0, cur)) return;
;     f32x4 acc[2][2][4][2];
; #pragma unroll
;     for (int a = 0; a < 2; ++a)
; #pragma unroll
;         for (int b = 0; b < 2; ++b)
; #pragma unroll
;             for (int m = 0; m < 4; ++m)
; #pragma unroll
;                 for (int n = 0; n < 2; ++n) acc[a][b][m][n] = (f32x4){0.f, 0.f, 0.f, 0.f};
;     bf16x8 At[4][2], B0[2][2], B1[2][2];
;     const char* cA = (const char*)g.A + (size_t)cur.pm * tstep; const char* cB = (const char*)g.Bt + (size_t)cur.pn * tstep;
;     S.a_ready(cur);
;     if constexpr (SP2) {
;         PG8_STAGE(PG8_SB(0, 0), cB, voffB); PG8_STAGE(PG8_SB(0, 1), cB + hstep, voffB); PG8_STAGE(PG8_SA(0, 0), cA, voffA); PG8_STAGE(PG8_SA(0, 1), cA + hstep, voffA);
;         if (wr == 1) PG8_BAR;
;         PG8_WAIT_V(2); PG8_BAR;
;         PG8_STAGE(PG8_SB(1, 0), cB + kstep, voffB); PG8_STAGE(PG8_SA(1, 0), cA + kstep, voffA); PG8_STAGE(PG8_SB(1, 1), cB + hstep + kstep, voffB);
;         PG8_WAIT_V(6); PG8_BAR;
;     } else {
;         PG8_STAGE(PG8_SB(0, 0), cB, voffB); PG8_STAGE(PG8_SA(0, 0), cA, voffA); PG8_STAGE(PG8_SB(0, 1), cB + hstep, voffB); PG8_STAGE(PG8_SA(0, 1), cA + hstep, voffA);
;         if (wr == 1) PG8_BAR;
;         PG8_WAIT_V(4); PG8_BAR;
;         PG8_STAGE(PG8_SB(1, 0), cB + kstep, voffB); PG8_STAGE(PG8_SA(1, 0), cA + kstep, voffA); PG8_STAGE(PG8_SB(1, 1), cB + hstep + kstep, voffB);
;         PG8_WAIT_V(6); PG8_BAR;
.LBB0_1019:
	s_lshl_b32 s10, s10, 5
	s_and_b32 s18, s10, 0x60
	s_mov_b64 s[10:11], 0x80
	s_add_i32 m0, s15, 0x18000
	v_lshl_add_u64 v[6:7], v[6:7], 0, s[10:11]
	s_lshl_b32 s13, s12, 13
	s_lshl_b32 s19, s18, 7
	s_waitcnt vmcnt(2)
	s_barrier
	global_load_lds_dwordx4 v[6:7], off
	v_lshl_add_u64 v[4:5], v[4:5], 0, s[10:11]
	s_add_i32 m0, s15, 0x1a000
	s_add_i32 s35, s15, 0x8000
	s_add_i32 s42, s15, 0xa000
	global_load_lds_dwordx4 v[4:5], off
	v_lshl_add_u64 v[0:1], v[0:1], 0, s[10:11]
	s_mov_b32 m0, s35
	s_add_u32 s16, s30, 0x80080
	global_load_lds_dwordx4 v[0:1], off
	v_lshl_add_u64 v[0:1], v[2:3], 0, s[10:11]
	s_mov_b32 m0, s42
	s_addc_u32 s17, s31, 0
	global_load_lds_dwordx4 v[0:1], off
	s_add_i32 m0, s15, 0x1c000
	v_lshl_add_u64 v[0:1], s[16:17], 0, v[132:133]
	global_load_lds_dwordx4 v[0:1], off
	v_lshl_add_u64 v[0:1], s[16:17], 0, v[128:129]
	s_add_i32 m0, s15, 0x1e000
	s_cmpk_lt_u32 s7, 0x100
	global_load_lds_dwordx4 v[0:1], off
	v_lshrrev_b32_e32 v1, 1, v9
	v_and_b32_e32 v2, 24, v1
	v_and_b32_e32 v0, 15, v9
	v_lshlrev_b32_e32 v1, 1, v2
	v_lshl_or_b32 v155, s12, 6, v0
	v_lshl_or_b32 v0, v0, 6, v1
	v_lshlrev_b32_e32 v1, 2, v9
	v_and_b32_e32 v1, 32, v1
	v_bitop3_b32 v3, v0, s13, v1 bitop3:0xde
	v_bitop3_b32 v159, v0, s19, v1 bitop3:0xde
	v_lshlrev_b32_e32 v0, 2, v2
	v_mov_b32_e32 v1, v133
	v_lshl_add_u64 v[136:137], s[0:1], 0, v[0:1]
	v_lshlrev_b32_e32 v0, 15, v13
	v_and_b32_e32 v0, 0xffff0000, v0
	v_lshl_add_u32 v0, v12, 12, v0
	v_and_b32_e32 v1, 1, v13
	v_lshl_or_b32 v0, v1, 6, v0
	v_lshl_add_u32 v138, v14, 1, v0
	v_lshlrev_b32_e32 v0, 15, v8
	v_and_b32_e32 v0, 0xffff0000, v0
	s_waitcnt vmcnt(6)
	v_lshl_add_u32 v0, v10, 12, v0
	v_and_b32_e32 v1, 1, v8
	s_cselect_b64 s[16:17], -1, 0
	v_lshl_or_b32 v0, v1, 6, v0
	s_add_i32 s43, 0, 0x10000
	s_add_i32 s44, 0, 0x14000
	s_sext_i32_i16 s46, s6
	v_or_b32_e32 v163, s18, v2
	v_mov_b32_e32 v139, v133
	v_lshl_add_u32 v140, v11, 1, v0
	v_mov_b32_e32 v141, v133
	v_mov_b64_e32 v[142:143], 0x580
	v_mov_b64_e32 v[144:145], 0x57f
	v_add_u32_e32 v167, s43, v159
	v_add_u32_e32 v171, s44, v159
	v_add_u32_e32 v175, 0, v3
	v_mov_b32_e32 v176, 0x358637bd
	s_movk_i32 s45, 0x2c00
	s_barrier
	s_mov_b32 s100, 0
	s_branch .LBB0_1022

; __device__ __forceinline__ void rows_rstd(const float* ssq, int row0, int fq, float scale, float (&rs)[2][4]) {
;     f32x4 pa[2][4], pb[2][4];
; #pragma unroll
;     for (int ai = 0; ai < 2; ++ai)
; #pragma unroll
;         for (int m = 0; m < 4; ++m) { const f32x4* p = (const f32x4*)(ssq + (size_t)(row0 + ai * HALF + m * 16) * 32 + 8 * fq); pa[ai][m] = p[0]; pb[ai][m] = p[1]; }
; #pragma unroll
;     for (int ai = 0; ai < 2; ++ai)
; #pragma unroll
;         for (int m = 0; m < 4; ++m) { const f32x4 a = pa[ai][m], c = pb[ai][m]; float s = ((a[0] + a[1]) + (a[2] + a[3])) + ((c[0] + c[1]) + (c[2] + c[3]));
;             s += __shfl_xor(s, 16); s += __shfl_xor(s, 32); rs[ai][m] = __builtin_amdgcn_rsqf(s * (1.0f / DMODEL) + RMS_EPS) * scale; }
;     __device__ __forceinline__ void operator()(const f32x4 (&acc)[2][2][4][2], const Unit& u, int wr, int wc, int fr, int fq) const {
;         const int row0 = u.pm * BM + wr * 64 + fr, col0 = u.pn * HALF + wc * 32 + 8 * fq;
;         float rs[2][4];
;         rows_rstd(ssq, row0, fq, 1.0f, rs);
.LBB0_1028:
	s_cmp_lg_u32 s100, 0
	s_cbranch_scc1 .Lrc7_fast
	v_lshrrev_b32_e32 v251, 6, v222
	v_and_b32_e32 v250, 15, v222
	v_lshl_or_b32 v251, v251, 4, v250
	v_lshlrev_b32_e32 v251, 5, v251
	v_add_u32_e32 v251, 0x20000, v251
	v_lshl_add_u32 v168, s26, 8, v155
	v_ashrrev_i32_e32 v169, 31, v168
	v_lshlrev_b64 v[146:147], 7, v[168:169]
	v_or_b32_e32 v164, 16, v168
	v_lshl_add_u64 v[146:147], v[136:137], 0, v[146:147]
	v_ashrrev_i32_e32 v165, 31, v164
	global_load_dwordx4 v[178:181], v[146:147], off
	global_load_dwordx4 v[182:185], v[146:147], off offset:16
	v_lshlrev_b64 v[146:147], 7, v[164:165]
	v_or_b32_e32 v160, 32, v168
	v_lshl_add_u64 v[146:147], v[136:137], 0, v[146:147]
	v_ashrrev_i32_e32 v161, 31, v160
	global_load_dwordx4 v[186:189], v[146:147], off
	global_load_dwordx4 v[190:193], v[146:147], off offset:16
	v_lshlrev_b64 v[146:147], 7, v[160:161]
	v_lshl_add_u64 v[146:147], v[136:137], 0, v[146:147]
	global_load_dwordx4 v[194:197], v[146:147], off
	global_load_dwordx4 v[198:201], v[146:147], off offset:16
	v_or_b32_e32 v156, 48, v168
	v_ashrrev_i32_e32 v157, 31, v156
	v_lshlrev_b64 v[146:147], 7, v[156:157]
	v_lshl_add_u64 v[146:147], v[136:137], 0, v[146:147]
	global_load_dwordx4 v[202:205], v[146:147], off
	global_load_dwordx4 v[206:209], v[146:147], off offset:16
	v_add_u32_e32 v152, 0x80, v168
	v_ashrrev_i32_e32 v153, 31, v152
	v_lshlrev_b64 v[146:147], 7, v[152:153]
	v_lshl_add_u64 v[146:147], v[136:137], 0, v[146:147]
	global_load_dwordx4 v[210:213], v[146:147], off
	global_load_dwordx4 v[214:217], v[146:147], off offset:16
	v_add_u32_e32 v150, 0x90, v168
	v_add_u32_e32 v148, 0xa0, v168
	v_add_u32_e32 v146, 0xb0, v168
	v_ashrrev_i32_e32 v151, 31, v150
	v_ashrrev_i32_e32 v149, 31, v148
	v_ashrrev_i32_e32 v147, 31, v146
	v_lshlrev_b64 v[218:219], 7, v[150:151]
	v_lshlrev_b64 v[220:221], 7, v[148:149]
	v_lshlrev_b64 v[226:227], 7, v[146:147]
	v_lshl_add_u64 v[228:229], v[136:137], 0, v[218:219]
	v_lshl_add_u64 v[234:235], v[136:137], 0, v[220:221]
	v_lshl_add_u64 v[242:243], v[136:137], 0, v[226:227]
	global_load_dwordx4 v[218:221], v[228:229], off
	s_nop 0
	global_load_dwordx4 v[226:229], v[228:229], off offset:16
	s_nop 0
	global_load_dwordx4 v[230:233], v[234:235], off
	s_nop 0
	global_load_dwordx4 v[234:237], v[234:235], off offset:16
	s_nop 0
	global_load_dwordx4 v[238:241], v[242:243], off
	s_nop 0
	global_load_dwordx4 v[242:245], v[242:243], off offset:16
	v_lshl_or_b32 v172, s46, 7, v163
	v_ashrrev_i32_e32 v173, 31, v172
	s_andn2_b64 vcc, exec, s[6:7]
	s_mov_b64 s[6:7], -1
	s_waitcnt vmcnt(0)
	v_mov_b32_e32 v246, v178
	v_mov_b32_e32 v247, v182
	v_mov_b32_e32 v182, v179
	v_mov_b32_e32 v178, v180
	v_mov_b32_e32 v179, v184
	v_mov_b32_e32 v184, v181
	v_pk_add_f32 v[180:181], v[246:247], v[182:183]
	v_pk_add_f32 v[178:179], v[178:179], v[184:185]
	v_mov_b32_e32 v182, v186
	v_mov_b32_e32 v183, v190
	v_mov_b32_e32 v190, v187
	v_mov_b32_e32 v184, v188
	v_mov_b32_e32 v185, v192
	v_mov_b32_e32 v192, v189
	v_pk_add_f32 v[178:179], v[180:181], v[178:179]
	v_pk_add_f32 v[180:181], v[182:183], v[190:191]
	v_pk_add_f32 v[182:183], v[184:185], v[192:193]
	v_add_f32_e32 v147, v178, v179
	v_mov_b32_e32 v186, v194
	v_mov_b32_e32 v187, v198
	v_mov_b32_e32 v198, v195
	v_mov_b32_e32 v188, v196
	v_mov_b32_e32 v189, v200
	v_mov_b32_e32 v200, v197
	v_pk_add_f32 v[178:179], v[180:181], v[182:183]
	ds_bpermute_b32 v149, v224, v147
	v_pk_add_f32 v[184:185], v[186:187], v[198:199]
	v_pk_add_f32 v[186:187], v[188:189], v[200:201]
	v_add_f32_e32 v151, v178, v179
	v_pk_add_f32 v[180:181], v[184:185], v[186:187]
	ds_bpermute_b32 v157, v224, v151
	v_add_f32_e32 v153, v180, v181
	ds_bpermute_b32 v158, v224, v153
	s_waitcnt lgkmcnt(2)
	v_add_f32_e32 v147, v147, v149
	v_mov_b32_e32 v194, v202
	v_mov_b32_e32 v195, v206
	v_mov_b32_e32 v206, v203
	v_mov_b32_e32 v196, v204
	v_mov_b32_e32 v197, v208
	v_mov_b32_e32 v208, v205
	ds_bpermute_b32 v149, v223, v147
	v_pk_add_f32 v[188:189], v[194:195], v[206:207]
	v_pk_add_f32 v[190:191], v[196:197], v[208:209]
	s_waitcnt lgkmcnt(2)
	v_add_f32_e32 v151, v151, v157
	v_pk_add_f32 v[182:183], v[188:189], v[190:191]
	ds_bpermute_b32 v157, v223, v151
	v_add_f32_e32 v154, v182, v183
	s_waitcnt lgkmcnt(2)
	v_add_f32_e32 v153, v153, v158
	ds_bpermute_b32 v161, v224, v154
	ds_bpermute_b32 v158, v223, v153
	s_waitcnt lgkmcnt(3)
	v_add_f32_e32 v147, v147, v149
	v_fmamk_f32 v147, v147, 0x3a000000, v176
	v_mov_b32_e32 v182, v210
	v_mov_b32_e32 v183, v214
	v_mov_b32_e32 v214, v211
	v_mov_b32_e32 v184, v212
	v_mov_b32_e32 v185, v216
	v_mov_b32_e32 v216, v213
	v_rsq_f32_e32 v178, v147
	s_waitcnt lgkmcnt(2)
	v_add_f32_e32 v147, v151, v157
	v_pk_add_f32 v[182:183], v[182:183], v[214:215]
	v_pk_add_f32 v[184:185], v[184:185], v[216:217]
	v_fmamk_f32 v147, v147, 0x3a000000, v176
	v_pk_add_f32 v[182:183], v[182:183], v[184:185]
	v_rsq_f32_e32 v180, v147
	s_waitcnt lgkmcnt(0)
	v_add_f32_e32 v147, v153, v158
	v_add_f32_e32 v149, v154, v161
	v_add_f32_e32 v153, v182, v183
	ds_bpermute_b32 v151, v223, v149
	ds_bpermute_b32 v154, v224, v153
	v_fmamk_f32 v147, v147, 0x3a000000, v176
	v_mov_b32_e32 v182, v218
	v_mov_b32_e32 v183, v226
	v_mov_b32_e32 v226, v219
	v_mov_b32_e32 v184, v220
	v_mov_b32_e32 v185, v228
	v_mov_b32_e32 v228, v221
	v_rsq_f32_e32 v174, v147
	s_waitcnt lgkmcnt(1)
	v_add_f32_e32 v147, v149, v151
	s_waitcnt lgkmcnt(0)
; __device__ __forceinline__ unsigned cvt_pk_bf16(float lo, float hi) { f32x2 v = {lo, hi}; bf16x2_t b = __builtin_convertvector(v, bf16x2_t); return __builtin_bit_cast(unsigned, b); }
; __device__ __forceinline__ float silu_f(float x) { return x * __builtin_amdgcn_rcpf(1.0f + __builtin_amdgcn_exp2f(-x * LOG2E)); }
; __device__ __forceinline__ void rows_rstd(const float* ssq, int row0, int fq, float scale, float (&rs)[2][4]) {
;     ...
;         for (int m = 0; m < 4; ++m) { const f32x4 a = pa[ai][m], c = pb[ai][m]; float s = ((a[0] + a[1]) + (a[2] + a[3])) + ((c[0] + c[1]) + (c[2] + c[3]));
;             s += __shfl_xor(s, 16); s += __shfl_xor(s, 32); rs[ai][m] = __builtin_amdgcn_rsqf(s * (1.0f / DMODEL) + RMS_EPS) * scale; }
;     __device__ __forceinline__ void operator()(const f32x4 (&acc)[2][2][4][2], const Unit& u, int wr, int wc, int fr, int fq) const {
;     ...
;             for (int m = 0; m < 4; ++m) { const int row = row0 + ai * HALF + m * 16; const float r = rs[ai][m];
;                 const f32x4 g0 = acc[ai][0][m][0] * r, g1 = acc[ai][0][m][1] * r, u0 = acc[ai][1][m][0] * r, u1 = acc[ai][1][m][1] * r;
;                 u32x4 w;
;                 w.x = cvt_pk_bf16(silu_f(g0[0]) * u0[0], silu_f(g0[1]) * u0[1]); w.y = cvt_pk_bf16(silu_f(g0[2]) * u0[2], silu_f(g0[3]) * u0[3]);
;                 w.z = cvt_pk_bf16(silu_f(g1[0]) * u1[0], silu_f(g1[1]) * u1[1]); w.w = cvt_pk_bf16(silu_f(g1[2]) * u1[2], silu_f(g1[3]) * u1[3]);
;                 *(u32x4*)(O + (size_t)row * ldo + col0) = w; }
	v_add_f32_e32 v149, v153, v154
	v_pk_add_f32 v[182:183], v[182:183], v[226:227]
	v_pk_add_f32 v[184:185], v[184:185], v[228:229]
	ds_bpermute_b32 v151, v223, v149
	v_pk_add_f32 v[182:183], v[182:183], v[184:185]
	v_mov_b32_e32 v184, v232
	v_add_f32_e32 v153, v182, v183
	ds_bpermute_b32 v154, v224, v153
	v_mov_b32_e32 v182, v230
	v_mov_b32_e32 v183, v234
	v_mov_b32_e32 v234, v231
	v_mov_b32_e32 v185, v236
	v_mov_b32_e32 v236, v233
	v_fmamk_f32 v147, v147, 0x3a000000, v176
	v_pk_add_f32 v[182:183], v[182:183], v[234:235]
	v_pk_add_f32 v[184:185], v[184:185], v[236:237]
	v_rsq_f32_e32 v170, v147
	s_waitcnt lgkmcnt(1)
	v_add_f32_e32 v147, v149, v151
	v_pk_add_f32 v[182:183], v[182:183], v[184:185]
	v_fmamk_f32 v147, v147, 0x3a000000, v176
	v_add_f32_e32 v151, v182, v183
	v_mov_b32_e32 v182, v238
	v_mov_b32_e32 v183, v242
	v_mov_b32_e32 v242, v239
	v_mov_b32_e32 v184, v240
	v_mov_b32_e32 v185, v244
	v_mov_b32_e32 v244, v241
	v_rsq_f32_e32 v166, v147
	s_waitcnt lgkmcnt(0)
	v_add_f32_e32 v147, v153, v154
	v_pk_add_f32 v[182:183], v[182:183], v[242:243]
	v_pk_add_f32 v[184:185], v[184:185], v[244:245]
	ds_bpermute_b32 v149, v223, v147
	ds_bpermute_b32 v153, v224, v151
	v_pk_add_f32 v[182:183], v[182:183], v[184:185]
	ds_write_b32 v251, v178 offset:0
	v_pk_mul_f32 v[124:125], v[124:125], v[178:179] op_sel_hi:[1,0]
	v_add_f32_e32 v154, v182, v183
	ds_bpermute_b32 v157, v224, v154
	s_waitcnt lgkmcnt(2)
	v_add_f32_e32 v147, v147, v149
	s_waitcnt lgkmcnt(1)
	v_add_f32_e32 v149, v151, v153
	ds_bpermute_b32 v151, v223, v149
	v_fmamk_f32 v147, v147, 0x3a000000, v176
	s_waitcnt lgkmcnt(1)
	v_add_f32_e32 v153, v154, v157
	ds_bpermute_b32 v154, v223, v153
	v_rsq_f32_e32 v162, v147
	s_waitcnt lgkmcnt(1)
	v_add_f32_e32 v147, v149, v151
	v_fmamk_f32 v147, v147, 0x3a000000, v176
	v_rsq_f32_e32 v158, v147
	s_waitcnt lgkmcnt(0)
	v_add_f32_e32 v147, v153, v154
	v_fmamk_f32 v147, v147, 0x3a000000, v176
	v_rsq_f32_e32 v154, v147
	v_mul_f32_e32 v147, 0xbfb8aa3b, v124
	v_exp_f32_e32 v147, v147
	v_mul_f32_e32 v149, 0xbfb8aa3b, v125
	v_exp_f32_e32 v149, v149
	v_pk_mul_f32 v[126:127], v[126:127], v[178:179] op_sel_hi:[1,0]
	v_add_f32_e32 v147, 1.0, v147
	v_pk_mul_f32 v[122:123], v[122:123], v[178:179] op_sel_hi:[1,0]
	v_pk_mul_f32 v[120:121], v[120:121], v[178:179] op_sel_hi:[1,0]
	v_pk_mul_f32 v[118:119], v[118:119], v[178:179] op_sel_hi:[1,0]
	v_pk_mul_f32 v[116:117], v[116:117], v[178:179] op_sel_hi:[1,0]
	v_pk_mul_f32 v[114:115], v[114:115], v[178:179] op_sel_hi:[1,0]
	v_pk_mul_f32 v[112:113], v[112:113], v[178:179] op_sel_hi:[1,0]
	v_rcp_f32_e32 v178, v147
	v_add_f32_e32 v147, 1.0, v149
	v_mul_f32_e32 v149, 0xbfb8aa3b, v126
	v_exp_f32_e32 v149, v149
	v_mul_f32_e32 v151, 0xbfb8aa3b, v127
	v_exp_f32_e32 v151, v151
	v_rcp_f32_e32 v179, v147
	v_add_f32_e32 v147, 1.0, v149
	v_rcp_f32_e32 v182, v147
	v_add_f32_e32 v147, 1.0, v151
	v_rcp_f32_e32 v183, v147
	v_pk_mul_f32 v[124:125], v[124:125], v[178:179]
	ds_write_b32 v251, v180 offset:4
	v_pk_mul_f32 v[108:109], v[108:109], v[180:181] op_sel_hi:[1,0]
	v_pk_mul_f32 v[116:117], v[116:117], v[124:125]
	v_pk_mul_f32 v[124:125], v[126:127], v[182:183]
	v_cvt_pk_bf16_f32 v116, v116, v117
	v_mul_f32_e32 v117, 0xbfb8aa3b, v120
	v_pk_mul_f32 v[118:119], v[118:119], v[124:125]
	v_exp_f32_e32 v124, v117
	v_mul_f32_e32 v117, 0xbfb8aa3b, v121
	v_exp_f32_e32 v125, v117
	v_cvt_pk_bf16_f32 v117, v118, v119
	v_add_f32_e32 v118, 1.0, v124
	v_mul_f32_e32 v124, 0xbfb8aa3b, v122
	v_add_f32_e32 v119, 1.0, v125
	v_mul_f32_e32 v125, 0xbfb8aa3b, v123
	v_exp_f32_e32 v124, v124
	v_exp_f32_e32 v125, v125
	v_rcp_f32_e32 v118, v118
	v_rcp_f32_e32 v119, v119
	v_add_f32_e32 v124, 1.0, v124
	v_add_f32_e32 v125, 1.0, v125
	v_rcp_f32_e32 v124, v124
	v_rcp_f32_e32 v125, v125
	v_pk_mul_f32 v[118:119], v[120:121], v[118:119]
	v_pk_mul_f32 v[110:111], v[110:111], v[180:181] op_sel_hi:[1,0]
	v_pk_mul_f32 v[112:113], v[112:113], v[118:119]
	v_pk_mul_f32 v[100:101], v[100:101], v[180:181] op_sel_hi:[1,0]
	v_cvt_pk_bf16_f32 v118, v112, v113
	v_pk_mul_f32 v[112:113], v[122:123], v[124:125]
	v_pk_mul_f32 v[104:105], v[104:105], v[180:181] op_sel_hi:[1,0]
	v_pk_mul_f32 v[112:113], v[114:115], v[112:113]
	v_lshlrev_b64 v[114:115], 1, v[172:173]
	v_cvt_pk_bf16_f32 v119, v112, v113
	v_mov_b64_e32 v[112:113], s[38:39]
	v_mad_i64_i32 v[120:121], s[12:13], v168, s45, v[112:113]
	v_lshl_add_u64 v[120:121], v[120:121], 0, v[114:115]
	global_store_dwordx4 v[120:121], v[116:119], off
	v_pk_mul_f32 v[102:103], v[102:103], v[180:181] op_sel_hi:[1,0]
	v_pk_mul_f32 v[106:107], v[106:107], v[180:181] op_sel_hi:[1,0]
	v_pk_mul_f32 v[116:117], v[98:99], v[180:181] op_sel_hi:[1,0]
	v_mul_f32_e32 v98, 0xbfb8aa3b, v108
	v_exp_f32_e32 v118, v98
	v_mul_f32_e32 v98, 0xbfb8aa3b, v109
	v_exp_f32_e32 v119, v98
	v_pk_mul_f32 v[98:99], v[96:97], v[180:181] op_sel_hi:[1,0]
	v_add_f32_e32 v96, 1.0, v118
	v_mul_f32_e32 v118, 0xbfb8aa3b, v110
	v_add_f32_e32 v97, 1.0, v119
	v_mul_f32_e32 v119, 0xbfb8aa3b, v111
	v_exp_f32_e32 v118, v118
	v_exp_f32_e32 v119, v119
	v_rcp_f32_e32 v96, v96
	v_rcp_f32_e32 v97, v97
	v_add_f32_e32 v118, 1.0, v118
	v_add_f32_e32 v119, 1.0, v119
	v_rcp_f32_e32 v118, v118
	v_rcp_f32_e32 v119, v119
	v_pk_mul_f32 v[96:97], v[108:109], v[96:97]
	ds_write_b32 v251, v174 offset:8
	v_pk_mul_f32 v[92:93], v[92:93], v[174:175] op_sel_hi:[1,0]
	v_pk_mul_f32 v[96:97], v[100:101], v[96:97]
	v_pk_mul_f32 v[100:101], v[110:111], v[118:119]
	v_cvt_pk_bf16_f32 v96, v96, v97
	v_mul_f32_e32 v97, 0xbfb8aa3b, v104
	v_pk_mul_f32 v[100:101], v[102:103], v[100:101]
	v_exp_f32_e32 v102, v97
	v_mul_f32_e32 v97, 0xbfb8aa3b, v105
	v_exp_f32_e32 v103, v97
	v_cvt_pk_bf16_f32 v97, v100, v101
; __device__ __forceinline__ unsigned cvt_pk_bf16(float lo, float hi) { f32x2 v = {lo, hi}; bf16x2_t b = __builtin_convertvector(v, bf16x2_t); return __builtin_bit_cast(unsigned, b); }
; __device__ __forceinline__ float silu_f(float x) { return x * __builtin_amdgcn_rcpf(1.0f + __builtin_amdgcn_exp2f(-x * LOG2E)); }
;     __device__ __forceinline__ void operator()(const f32x4 (&acc)[2][2][4][2], const Unit& u, int wr, int wc, int fr, int fq) const {
;     ...
;             for (int m = 0; m < 4; ++m) { const int row = row0 + ai * HALF + m * 16; const float r = rs[ai][m];
;                 const f32x4 g0 = acc[ai][0][m][0] * r, g1 = acc[ai][0][m][1] * r, u0 = acc[ai][1][m][0] * r, u1 = acc[ai][1][m][1] * r;
;                 u32x4 w;
;                 w.x = cvt_pk_bf16(silu_f(g0[0]) * u0[0], silu_f(g0[1]) * u0[1]); w.y = cvt_pk_bf16(silu_f(g0[2]) * u0[2], silu_f(g0[3]) * u0[3]);
;                 w.z = cvt_pk_bf16(silu_f(g1[0]) * u1[0], silu_f(g1[1]) * u1[1]); w.w = cvt_pk_bf16(silu_f(g1[2]) * u1[2], silu_f(g1[3]) * u1[3]);
;                 *(u32x4*)(O + (size_t)row * ldo + col0) = w; }
	v_add_f32_e32 v100, 1.0, v102
	v_mul_f32_e32 v102, 0xbfb8aa3b, v106
	v_add_f32_e32 v101, 1.0, v103
	v_mul_f32_e32 v103, 0xbfb8aa3b, v107
	v_exp_f32_e32 v102, v102
	v_exp_f32_e32 v103, v103
	v_rcp_f32_e32 v100, v100
	v_rcp_f32_e32 v101, v101
	v_add_f32_e32 v102, 1.0, v102
	v_add_f32_e32 v103, 1.0, v103
	v_rcp_f32_e32 v102, v102
	v_rcp_f32_e32 v103, v103
	v_pk_mul_f32 v[100:101], v[104:105], v[100:101]
	v_pk_mul_f32 v[94:95], v[94:95], v[174:175] op_sel_hi:[1,0]
	v_pk_mul_f32 v[98:99], v[98:99], v[100:101]
	v_pk_mul_f32 v[100:101], v[106:107], v[102:103]
	v_cvt_pk_bf16_f32 v98, v98, v99
	v_pk_mul_f32 v[100:101], v[116:117], v[100:101]
	v_pk_mul_f32 v[84:85], v[84:85], v[174:175] op_sel_hi:[1,0]
	v_cvt_pk_bf16_f32 v99, v100, v101
	v_mad_i64_i32 v[100:101], s[12:13], v164, s45, v[112:113]
	v_lshl_add_u64 v[100:101], v[100:101], 0, v[114:115]
	global_store_dwordx4 v[100:101], v[96:99], off
	v_pk_mul_f32 v[88:89], v[88:89], v[174:175] op_sel_hi:[1,0]
	v_pk_mul_f32 v[86:87], v[86:87], v[174:175] op_sel_hi:[1,0]
	v_pk_mul_f32 v[96:97], v[82:83], v[174:175] op_sel_hi:[1,0]
	v_mul_f32_e32 v82, 0xbfb8aa3b, v92
	v_exp_f32_e32 v98, v82
	v_mul_f32_e32 v82, 0xbfb8aa3b, v93
	v_exp_f32_e32 v99, v82
	v_pk_mul_f32 v[82:83], v[80:81], v[174:175] op_sel_hi:[1,0]
	v_add_f32_e32 v80, 1.0, v98
	v_mul_f32_e32 v98, 0xbfb8aa3b, v94
	v_add_f32_e32 v81, 1.0, v99
	v_mul_f32_e32 v99, 0xbfb8aa3b, v95
	v_exp_f32_e32 v98, v98
	v_exp_f32_e32 v99, v99
	v_rcp_f32_e32 v80, v80
	v_rcp_f32_e32 v81, v81
	v_add_f32_e32 v98, 1.0, v98
	v_add_f32_e32 v99, 1.0, v99
	v_rcp_f32_e32 v98, v98
	v_rcp_f32_e32 v99, v99
	v_pk_mul_f32 v[80:81], v[92:93], v[80:81]
	v_pk_mul_f32 v[90:91], v[90:91], v[174:175] op_sel_hi:[1,0]
	v_pk_mul_f32 v[80:81], v[84:85], v[80:81]
	v_pk_mul_f32 v[84:85], v[94:95], v[98:99]
	v_cvt_pk_bf16_f32 v80, v80, v81
	v_mul_f32_e32 v81, 0xbfb8aa3b, v88
	v_pk_mul_f32 v[84:85], v[86:87], v[84:85]
	v_exp_f32_e32 v86, v81
	v_mul_f32_e32 v81, 0xbfb8aa3b, v89
	v_exp_f32_e32 v87, v81
	v_cvt_pk_bf16_f32 v81, v84, v85
	v_add_f32_e32 v84, 1.0, v86
	v_mul_f32_e32 v86, 0xbfb8aa3b, v90
	v_add_f32_e32 v85, 1.0, v87
	v_mul_f32_e32 v87, 0xbfb8aa3b, v91
	v_exp_f32_e32 v86, v86
	v_exp_f32_e32 v87, v87
	v_rcp_f32_e32 v84, v84
	v_rcp_f32_e32 v85, v85
	v_add_f32_e32 v86, 1.0, v86
	v_add_f32_e32 v87, 1.0, v87
	v_rcp_f32_e32 v86, v86
	v_rcp_f32_e32 v87, v87
	v_pk_mul_f32 v[84:85], v[88:89], v[84:85]
	ds_write_b32 v251, v170 offset:12
	v_pk_mul_f32 v[76:77], v[76:77], v[170:171] op_sel_hi:[1,0]
	v_pk_mul_f32 v[82:83], v[82:83], v[84:85]
	v_pk_mul_f32 v[84:85], v[90:91], v[86:87]
	v_cvt_pk_bf16_f32 v82, v82, v83
	v_pk_mul_f32 v[84:85], v[96:97], v[84:85]
	v_pk_mul_f32 v[78:79], v[78:79], v[170:171] op_sel_hi:[1,0]
	v_cvt_pk_bf16_f32 v83, v84, v85
	v_mad_i64_i32 v[84:85], s[12:13], v160, s45, v[112:113]
	v_lshl_add_u64 v[84:85], v[84:85], 0, v[114:115]
	global_store_dwordx4 v[84:85], v[80:83], off
	v_pk_mul_f32 v[68:69], v[68:69], v[170:171] op_sel_hi:[1,0]
	v_pk_mul_f32 v[72:73], v[72:73], v[170:171] op_sel_hi:[1,0]
	v_pk_mul_f32 v[80:81], v[66:67], v[170:171] op_sel_hi:[1,0]
	v_mul_f32_e32 v66, 0xbfb8aa3b, v76
	v_exp_f32_e32 v82, v66
	v_mul_f32_e32 v66, 0xbfb8aa3b, v77
	v_exp_f32_e32 v83, v66
	v_pk_mul_f32 v[66:67], v[64:65], v[170:171] op_sel_hi:[1,0]
	v_add_f32_e32 v64, 1.0, v82
	v_mul_f32_e32 v82, 0xbfb8aa3b, v78
	v_add_f32_e32 v65, 1.0, v83
	v_mul_f32_e32 v83, 0xbfb8aa3b, v79
	v_exp_f32_e32 v82, v82
	v_exp_f32_e32 v83, v83
	v_rcp_f32_e32 v64, v64
	v_rcp_f32_e32 v65, v65
	v_add_f32_e32 v82, 1.0, v82
	v_add_f32_e32 v83, 1.0, v83
	v_rcp_f32_e32 v82, v82
	v_rcp_f32_e32 v83, v83
	v_pk_mul_f32 v[64:65], v[76:77], v[64:65]
	v_pk_mul_f32 v[70:71], v[70:71], v[170:171] op_sel_hi:[1,0]
	v_pk_mul_f32 v[64:65], v[68:69], v[64:65]
	v_pk_mul_f32 v[68:69], v[78:79], v[82:83]
	v_cvt_pk_bf16_f32 v64, v64, v65
	v_mul_f32_e32 v65, 0xbfb8aa3b, v72
	v_pk_mul_f32 v[68:69], v[70:71], v[68:69]
	v_exp_f32_e32 v70, v65
	v_mul_f32_e32 v65, 0xbfb8aa3b, v73
	v_exp_f32_e32 v71, v65
	v_pk_mul_f32 v[74:75], v[74:75], v[170:171] op_sel_hi:[1,0]
	v_cvt_pk_bf16_f32 v65, v68, v69
	v_add_f32_e32 v68, 1.0, v70
	v_add_f32_e32 v69, 1.0, v71
	v_mul_f32_e32 v70, 0xbfb8aa3b, v74
	v_mul_f32_e32 v71, 0xbfb8aa3b, v75
	v_exp_f32_e32 v70, v70
	v_exp_f32_e32 v71, v71
	v_rcp_f32_e32 v68, v68
	v_rcp_f32_e32 v69, v69
	v_add_f32_e32 v70, 1.0, v70
	v_add_f32_e32 v71, 1.0, v71
	v_rcp_f32_e32 v70, v70
	v_rcp_f32_e32 v71, v71
	v_pk_mul_f32 v[68:69], v[72:73], v[68:69]
	ds_write_b32 v251, v166 offset:16
	v_pk_mul_f32 v[60:61], v[60:61], v[166:167] op_sel_hi:[1,0]
	v_pk_mul_f32 v[66:67], v[66:67], v[68:69]
	v_pk_mul_f32 v[68:69], v[74:75], v[70:71]
	v_cvt_pk_bf16_f32 v66, v66, v67
	v_pk_mul_f32 v[68:69], v[80:81], v[68:69]
	v_pk_mul_f32 v[62:63], v[62:63], v[166:167] op_sel_hi:[1,0]
	v_cvt_pk_bf16_f32 v67, v68, v69
	v_mad_i64_i32 v[68:69], s[12:13], v156, s45, v[112:113]
	v_lshl_add_u64 v[68:69], v[68:69], 0, v[114:115]
	global_store_dwordx4 v[68:69], v[64:67], off
	v_pk_mul_f32 v[52:53], v[52:53], v[166:167] op_sel_hi:[1,0]
	v_pk_mul_f32 v[56:57], v[56:57], v[166:167] op_sel_hi:[1,0]
	v_pk_mul_f32 v[64:65], v[50:51], v[166:167] op_sel_hi:[1,0]
	v_mul_f32_e32 v50, 0xbfb8aa3b, v60
	v_exp_f32_e32 v66, v50
	v_mul_f32_e32 v50, 0xbfb8aa3b, v61
	v_exp_f32_e32 v67, v50
	v_pk_mul_f32 v[50:51], v[48:49], v[166:167] op_sel_hi:[1,0]
	v_add_f32_e32 v48, 1.0, v66
	v_mul_f32_e32 v66, 0xbfb8aa3b, v62
	v_add_f32_e32 v49, 1.0, v67
	v_mul_f32_e32 v67, 0xbfb8aa3b, v63
	v_exp_f32_e32 v66, v66
	v_exp_f32_e32 v67, v67
	v_rcp_f32_e32 v48, v48
	v_rcp_f32_e32 v49, v49
	v_add_f32_e32 v66, 1.0, v66
	v_add_f32_e32 v67, 1.0, v67
	v_rcp_f32_e32 v66, v66
	v_rcp_f32_e32 v67, v67
; __device__ __forceinline__ unsigned cvt_pk_bf16(float lo, float hi) { f32x2 v = {lo, hi}; bf16x2_t b = __builtin_convertvector(v, bf16x2_t); return __builtin_bit_cast(unsigned, b); }
; __device__ __forceinline__ float silu_f(float x) { return x * __builtin_amdgcn_rcpf(1.0f + __builtin_amdgcn_exp2f(-x * LOG2E)); }
;     __device__ __forceinline__ void operator()(const f32x4 (&acc)[2][2][4][2], const Unit& u, int wr, int wc, int fr, int fq) const {
;     ...
;             for (int m = 0; m < 4; ++m) { const int row = row0 + ai * HALF + m * 16; const float r = rs[ai][m];
;                 const f32x4 g0 = acc[ai][0][m][0] * r, g1 = acc[ai][0][m][1] * r, u0 = acc[ai][1][m][0] * r, u1 = acc[ai][1][m][1] * r;
;                 u32x4 w;
;                 w.x = cvt_pk_bf16(silu_f(g0[0]) * u0[0], silu_f(g0[1]) * u0[1]); w.y = cvt_pk_bf16(silu_f(g0[2]) * u0[2], silu_f(g0[3]) * u0[3]);
;                 w.z = cvt_pk_bf16(silu_f(g1[0]) * u1[0], silu_f(g1[1]) * u1[1]); w.w = cvt_pk_bf16(silu_f(g1[2]) * u1[2], silu_f(g1[3]) * u1[3]);
;                 *(u32x4*)(O + (size_t)row * ldo + col0) = w; }
	v_pk_mul_f32 v[48:49], v[60:61], v[48:49]
	v_pk_mul_f32 v[54:55], v[54:55], v[166:167] op_sel_hi:[1,0]
	v_pk_mul_f32 v[48:49], v[52:53], v[48:49]
	v_pk_mul_f32 v[52:53], v[62:63], v[66:67]
	v_cvt_pk_bf16_f32 v48, v48, v49
	v_mul_f32_e32 v49, 0xbfb8aa3b, v56
	v_pk_mul_f32 v[52:53], v[54:55], v[52:53]
	v_exp_f32_e32 v54, v49
	v_mul_f32_e32 v49, 0xbfb8aa3b, v57
	v_exp_f32_e32 v55, v49
	v_pk_mul_f32 v[58:59], v[58:59], v[166:167] op_sel_hi:[1,0]
	v_cvt_pk_bf16_f32 v49, v52, v53
	v_add_f32_e32 v52, 1.0, v54
	v_add_f32_e32 v53, 1.0, v55
	v_mul_f32_e32 v54, 0xbfb8aa3b, v58
	v_mul_f32_e32 v55, 0xbfb8aa3b, v59
	v_exp_f32_e32 v54, v54
	v_exp_f32_e32 v55, v55
	v_rcp_f32_e32 v52, v52
	v_rcp_f32_e32 v53, v53
	v_add_f32_e32 v54, 1.0, v54
	v_add_f32_e32 v55, 1.0, v55
	v_rcp_f32_e32 v54, v54
	v_rcp_f32_e32 v55, v55
	v_pk_mul_f32 v[52:53], v[56:57], v[52:53]
	ds_write_b32 v251, v162 offset:20
	v_pk_mul_f32 v[44:45], v[44:45], v[162:163] op_sel_hi:[1,0]
	v_pk_mul_f32 v[50:51], v[50:51], v[52:53]
	v_pk_mul_f32 v[52:53], v[58:59], v[54:55]
	v_cvt_pk_bf16_f32 v50, v50, v51
	v_pk_mul_f32 v[52:53], v[64:65], v[52:53]
	v_pk_mul_f32 v[46:47], v[46:47], v[162:163] op_sel_hi:[1,0]
	v_cvt_pk_bf16_f32 v51, v52, v53
	v_mad_i64_i32 v[52:53], s[12:13], v152, s45, v[112:113]
	v_lshl_add_u64 v[52:53], v[52:53], 0, v[114:115]
	global_store_dwordx4 v[52:53], v[48:51], off
	v_pk_mul_f32 v[36:37], v[36:37], v[162:163] op_sel_hi:[1,0]
	v_pk_mul_f32 v[40:41], v[40:41], v[162:163] op_sel_hi:[1,0]
	v_pk_mul_f32 v[48:49], v[34:35], v[162:163] op_sel_hi:[1,0]
	v_mul_f32_e32 v34, 0xbfb8aa3b, v44
	v_exp_f32_e32 v50, v34
	v_mul_f32_e32 v34, 0xbfb8aa3b, v45
	v_exp_f32_e32 v51, v34
	v_pk_mul_f32 v[34:35], v[32:33], v[162:163] op_sel_hi:[1,0]
	v_add_f32_e32 v32, 1.0, v50
	v_mul_f32_e32 v50, 0xbfb8aa3b, v46
	v_add_f32_e32 v33, 1.0, v51
	v_mul_f32_e32 v51, 0xbfb8aa3b, v47
	v_exp_f32_e32 v50, v50
	v_exp_f32_e32 v51, v51
	v_rcp_f32_e32 v32, v32
	v_rcp_f32_e32 v33, v33
	v_add_f32_e32 v50, 1.0, v50
	v_add_f32_e32 v51, 1.0, v51
	v_rcp_f32_e32 v50, v50
	v_rcp_f32_e32 v51, v51
	v_pk_mul_f32 v[32:33], v[44:45], v[32:33]
	v_pk_mul_f32 v[38:39], v[38:39], v[162:163] op_sel_hi:[1,0]
	v_pk_mul_f32 v[32:33], v[36:37], v[32:33]
	v_pk_mul_f32 v[36:37], v[46:47], v[50:51]
	v_cvt_pk_bf16_f32 v32, v32, v33
	v_mul_f32_e32 v33, 0xbfb8aa3b, v40
	v_pk_mul_f32 v[36:37], v[38:39], v[36:37]
	v_exp_f32_e32 v38, v33
	v_mul_f32_e32 v33, 0xbfb8aa3b, v41
	v_exp_f32_e32 v39, v33
	v_pk_mul_f32 v[42:43], v[42:43], v[162:163] op_sel_hi:[1,0]
	v_cvt_pk_bf16_f32 v33, v36, v37
	v_add_f32_e32 v36, 1.0, v38
	v_add_f32_e32 v37, 1.0, v39
	v_mul_f32_e32 v38, 0xbfb8aa3b, v42
	v_mul_f32_e32 v39, 0xbfb8aa3b, v43
	v_exp_f32_e32 v38, v38
	v_exp_f32_e32 v39, v39
	v_rcp_f32_e32 v36, v36
	v_rcp_f32_e32 v37, v37
	v_add_f32_e32 v38, 1.0, v38
	v_add_f32_e32 v39, 1.0, v39
	v_rcp_f32_e32 v38, v38
	v_rcp_f32_e32 v39, v39
	v_pk_mul_f32 v[36:37], v[40:41], v[36:37]
	ds_write_b32 v251, v158 offset:24
	v_pk_mul_f32 v[28:29], v[28:29], v[158:159] op_sel_hi:[1,0]
	v_pk_mul_f32 v[34:35], v[34:35], v[36:37]
	v_pk_mul_f32 v[36:37], v[42:43], v[38:39]
	v_cvt_pk_bf16_f32 v34, v34, v35
	v_pk_mul_f32 v[36:37], v[48:49], v[36:37]
	v_pk_mul_f32 v[30:31], v[30:31], v[158:159] op_sel_hi:[1,0]
	v_cvt_pk_bf16_f32 v35, v36, v37
	v_mad_i64_i32 v[36:37], s[12:13], v150, s45, v[112:113]
	v_lshl_add_u64 v[36:37], v[36:37], 0, v[114:115]
	global_store_dwordx4 v[36:37], v[32:35], off
	v_pk_mul_f32 v[20:21], v[20:21], v[158:159] op_sel_hi:[1,0]
	v_pk_mul_f32 v[24:25], v[24:25], v[158:159] op_sel_hi:[1,0]
	v_pk_mul_f32 v[32:33], v[18:19], v[158:159] op_sel_hi:[1,0]
	v_mul_f32_e32 v18, 0xbfb8aa3b, v28
	v_exp_f32_e32 v34, v18
	v_mul_f32_e32 v18, 0xbfb8aa3b, v29
	v_exp_f32_e32 v35, v18
	v_pk_mul_f32 v[18:19], v[16:17], v[158:159] op_sel_hi:[1,0]
	v_add_f32_e32 v16, 1.0, v34
	v_mul_f32_e32 v34, 0xbfb8aa3b, v30
	v_add_f32_e32 v17, 1.0, v35
	v_mul_f32_e32 v35, 0xbfb8aa3b, v31
	v_exp_f32_e32 v34, v34
	v_exp_f32_e32 v35, v35
	v_rcp_f32_e32 v16, v16
	v_rcp_f32_e32 v17, v17
	v_add_f32_e32 v34, 1.0, v34
	v_add_f32_e32 v35, 1.0, v35
	v_rcp_f32_e32 v34, v34
	v_rcp_f32_e32 v35, v35
	v_pk_mul_f32 v[16:17], v[28:29], v[16:17]
	v_pk_mul_f32 v[22:23], v[22:23], v[158:159] op_sel_hi:[1,0]
	v_pk_mul_f32 v[16:17], v[20:21], v[16:17]
	v_pk_mul_f32 v[20:21], v[30:31], v[34:35]
	v_cvt_pk_bf16_f32 v16, v16, v17
	v_mul_f32_e32 v17, 0xbfb8aa3b, v24
	v_pk_mul_f32 v[20:21], v[22:23], v[20:21]
	v_exp_f32_e32 v22, v17
	v_mul_f32_e32 v17, 0xbfb8aa3b, v25
	v_exp_f32_e32 v23, v17
	v_pk_mul_f32 v[26:27], v[26:27], v[158:159] op_sel_hi:[1,0]
	v_cvt_pk_bf16_f32 v17, v20, v21
	v_add_f32_e32 v20, 1.0, v22
	v_add_f32_e32 v21, 1.0, v23
	v_mul_f32_e32 v22, 0xbfb8aa3b, v26
	v_mul_f32_e32 v23, 0xbfb8aa3b, v27
	v_exp_f32_e32 v22, v22
	v_exp_f32_e32 v23, v23
	v_rcp_f32_e32 v20, v20
	v_rcp_f32_e32 v21, v21
	v_add_f32_e32 v22, 1.0, v22
	v_add_f32_e32 v23, 1.0, v23
	v_rcp_f32_e32 v22, v22
	v_rcp_f32_e32 v23, v23
	v_pk_mul_f32 v[20:21], v[24:25], v[20:21]
	ds_write_b32 v251, v154 offset:28
	v_pk_mul_f32 v[12:13], v[12:13], v[154:155] op_sel_hi:[1,0]
	s_mov_b32 s100, 1
	s_branch .Lrc7_join
; __device__ __forceinline__ unsigned cvt_pk_bf16(float lo, float hi) { f32x2 v = {lo, hi}; bf16x2_t b = __builtin_convertvector(v, bf16x2_t); return __builtin_bit_cast(unsigned, b); }
; __device__ __forceinline__ float silu_f(float x) { return x * __builtin_amdgcn_rcpf(1.0f + __builtin_amdgcn_exp2f(-x * LOG2E)); }
;     __device__ __forceinline__ void operator()(const f32x4 (&acc)[2][2][4][2], const Unit& u, int wr, int wc, int fr, int fq) const {
;         const int row0 = u.pm * BM + wr * 64 + fr, col0 = u.pn * HALF + wc * 32 + 8 * fq;
;         float rs[2][4];
;         rows_rstd(ssq, row0, fq, 1.0f, rs);
; #pragma unroll
;         for (int ai = 0; ai < 2; ++ai)
; #pragma unroll
;             for (int m = 0; m < 4; ++m) { const int row = row0 + ai * HALF + m * 16; const float r = rs[ai][m];
;                 const f32x4 g0 = acc[ai][0][m][0] * r, g1 = acc[ai][0][m][1] * r, u0 = acc[ai][1][m][0] * r, u1 = acc[ai][1][m][1] * r;
;                 u32x4 w;
;                 w.x = cvt_pk_bf16(silu_f(g0[0]) * u0[0], silu_f(g0[1]) * u0[1]); w.y = cvt_pk_bf16(silu_f(g0[2]) * u0[2], silu_f(g0[3]) * u0[3]);
;                 w.z = cvt_pk_bf16(silu_f(g1[0]) * u1[0], silu_f(g1[1]) * u1[1]); w.w = cvt_pk_bf16(silu_f(g1[2]) * u1[2], silu_f(g1[3]) * u1[3]);
;                 *(u32x4*)(O + (size_t)row * ldo + col0) = w; }
.Lrc7_fast:
	v_lshrrev_b32_e32 v251, 6, v222
	v_and_b32_e32 v250, 15, v222
	v_lshl_or_b32 v251, v251, 4, v250
	v_lshlrev_b32_e32 v251, 5, v251
	v_add_u32_e32 v251, 0x20000, v251
	ds_read_b32 v169, v251
	ds_read_b32 v165, v251 offset:4
	ds_read_b32 v181, v251 offset:8
	ds_read_b32 v184, v251 offset:12
	ds_read_b32 v185, v251 offset:16
	ds_read_b32 v161, v251 offset:20
	ds_read_b32 v186, v251 offset:24
	ds_read_b32 v187, v251 offset:28
	s_waitcnt lgkmcnt(0)
	v_lshl_add_u32 v168, s26, 8, v155
	v_or_b32_e32 v164, 16, v168
	v_or_b32_e32 v160, 32, v168
	v_or_b32_e32 v156, 48, v168
	v_add_u32_e32 v152, 0x80, v168
	v_add_u32_e32 v150, 0x90, v168
	v_add_u32_e32 v148, 0xa0, v168
	v_add_u32_e32 v146, 0xb0, v168
	s_nop 0
	s_nop 0
	s_nop 0
	s_nop 0
	s_nop 0
	v_lshl_or_b32 v172, s46, 7, v163
	v_ashrrev_i32_e32 v173, 31, v172
	s_andn2_b64 vcc, exec, s[6:7]
	s_mov_b64 s[6:7], -1
	s_waitcnt lgkmcnt(2)
	s_waitcnt lgkmcnt(2)
	s_waitcnt lgkmcnt(2)
	s_waitcnt lgkmcnt(3)
	s_waitcnt lgkmcnt(2)
	s_waitcnt lgkmcnt(0)
	s_waitcnt lgkmcnt(1)
	s_waitcnt lgkmcnt(0)
	s_waitcnt lgkmcnt(1)
	s_waitcnt lgkmcnt(0)
	v_mov_b32_e32 v178, v169
	v_pk_mul_f32 v[124:125], v[124:125], v[178:179] op_sel_hi:[1,0]
	s_waitcnt lgkmcnt(2)
	s_waitcnt lgkmcnt(1)
	s_waitcnt lgkmcnt(1)
	s_waitcnt lgkmcnt(1)
	s_waitcnt lgkmcnt(0)
	v_mul_f32_e32 v147, 0xbfb8aa3b, v124
	v_exp_f32_e32 v147, v147
	v_mul_f32_e32 v149, 0xbfb8aa3b, v125
	v_exp_f32_e32 v149, v149
	v_pk_mul_f32 v[126:127], v[126:127], v[178:179] op_sel_hi:[1,0]
	v_add_f32_e32 v147, 1.0, v147
	v_pk_mul_f32 v[122:123], v[122:123], v[178:179] op_sel_hi:[1,0]
	v_pk_mul_f32 v[120:121], v[120:121], v[178:179] op_sel_hi:[1,0]
	v_pk_mul_f32 v[118:119], v[118:119], v[178:179] op_sel_hi:[1,0]
	v_pk_mul_f32 v[116:117], v[116:117], v[178:179] op_sel_hi:[1,0]
	v_pk_mul_f32 v[114:115], v[114:115], v[178:179] op_sel_hi:[1,0]
	v_pk_mul_f32 v[112:113], v[112:113], v[178:179] op_sel_hi:[1,0]
	v_rcp_f32_e32 v178, v147
	v_add_f32_e32 v147, 1.0, v149
	v_mul_f32_e32 v149, 0xbfb8aa3b, v126
	v_exp_f32_e32 v149, v149
	v_mul_f32_e32 v151, 0xbfb8aa3b, v127
	v_exp_f32_e32 v151, v151
	v_rcp_f32_e32 v179, v147
	v_add_f32_e32 v147, 1.0, v149
	v_rcp_f32_e32 v182, v147
	v_add_f32_e32 v147, 1.0, v151
	v_rcp_f32_e32 v183, v147
	v_pk_mul_f32 v[124:125], v[124:125], v[178:179]
	v_mov_b32_e32 v180, v165
	v_pk_mul_f32 v[108:109], v[108:109], v[180:181] op_sel_hi:[1,0]
	v_pk_mul_f32 v[116:117], v[116:117], v[124:125]
	v_pk_mul_f32 v[124:125], v[126:127], v[182:183]
	v_cvt_pk_bf16_f32 v116, v116, v117
	v_mul_f32_e32 v117, 0xbfb8aa3b, v120
	v_pk_mul_f32 v[118:119], v[118:119], v[124:125]
	v_exp_f32_e32 v124, v117
	v_mul_f32_e32 v117, 0xbfb8aa3b, v121
	v_exp_f32_e32 v125, v117
	v_cvt_pk_bf16_f32 v117, v118, v119
	v_add_f32_e32 v118, 1.0, v124
	v_mul_f32_e32 v124, 0xbfb8aa3b, v122
	v_add_f32_e32 v119, 1.0, v125
	v_mul_f32_e32 v125, 0xbfb8aa3b, v123
	v_exp_f32_e32 v124, v124
	v_exp_f32_e32 v125, v125
	v_rcp_f32_e32 v118, v118
	v_rcp_f32_e32 v119, v119
	v_add_f32_e32 v124, 1.0, v124
	v_add_f32_e32 v125, 1.0, v125
	v_rcp_f32_e32 v124, v124
	v_rcp_f32_e32 v125, v125
	v_pk_mul_f32 v[118:119], v[120:121], v[118:119]
	v_pk_mul_f32 v[110:111], v[110:111], v[180:181] op_sel_hi:[1,0]
	v_pk_mul_f32 v[112:113], v[112:113], v[118:119]
	v_pk_mul_f32 v[100:101], v[100:101], v[180:181] op_sel_hi:[1,0]
	v_cvt_pk_bf16_f32 v118, v112, v113
	v_pk_mul_f32 v[112:113], v[122:123], v[124:125]
	v_pk_mul_f32 v[104:105], v[104:105], v[180:181] op_sel_hi:[1,0]
	v_pk_mul_f32 v[112:113], v[114:115], v[112:113]
	v_lshlrev_b64 v[114:115], 1, v[172:173]
	v_cvt_pk_bf16_f32 v119, v112, v113
	v_mov_b64_e32 v[112:113], s[38:39]
	v_mad_i64_i32 v[120:121], s[12:13], v168, s45, v[112:113]
	v_lshl_add_u64 v[120:121], v[120:121], 0, v[114:115]
	global_store_dwordx4 v[120:121], v[116:119], off
	v_pk_mul_f32 v[102:103], v[102:103], v[180:181] op_sel_hi:[1,0]
	v_pk_mul_f32 v[106:107], v[106:107], v[180:181] op_sel_hi:[1,0]
	v_pk_mul_f32 v[116:117], v[98:99], v[180:181] op_sel_hi:[1,0]
	v_mul_f32_e32 v98, 0xbfb8aa3b, v108
	v_exp_f32_e32 v118, v98
	v_mul_f32_e32 v98, 0xbfb8aa3b, v109
	v_exp_f32_e32 v119, v98
	v_pk_mul_f32 v[98:99], v[96:97], v[180:181] op_sel_hi:[1,0]
	v_add_f32_e32 v96, 1.0, v118
	v_mul_f32_e32 v118, 0xbfb8aa3b, v110
	v_add_f32_e32 v97, 1.0, v119
	v_mul_f32_e32 v119, 0xbfb8aa3b, v111
	v_exp_f32_e32 v118, v118
	v_exp_f32_e32 v119, v119
	v_rcp_f32_e32 v96, v96
	v_rcp_f32_e32 v97, v97
	v_add_f32_e32 v118, 1.0, v118
	v_add_f32_e32 v119, 1.0, v119
	v_rcp_f32_e32 v118, v118
	v_rcp_f32_e32 v119, v119
	v_pk_mul_f32 v[96:97], v[108:109], v[96:97]
	v_mov_b32_e32 v174, v181
	v_pk_mul_f32 v[92:93], v[92:93], v[174:175] op_sel_hi:[1,0]
	v_pk_mul_f32 v[96:97], v[100:101], v[96:97]
	v_pk_mul_f32 v[100:101], v[110:111], v[118:119]
	v_cvt_pk_bf16_f32 v96, v96, v97
	v_mul_f32_e32 v97, 0xbfb8aa3b, v104
	v_pk_mul_f32 v[100:101], v[102:103], v[100:101]
	v_exp_f32_e32 v102, v97
	v_mul_f32_e32 v97, 0xbfb8aa3b, v105
	v_exp_f32_e32 v103, v97
	v_cvt_pk_bf16_f32 v97, v100, v101
	v_add_f32_e32 v100, 1.0, v102
	v_mul_f32_e32 v102, 0xbfb8aa3b, v106
	v_add_f32_e32 v101, 1.0, v103
	v_mul_f32_e32 v103, 0xbfb8aa3b, v107
	v_exp_f32_e32 v102, v102
	v_exp_f32_e32 v103, v103
	v_rcp_f32_e32 v100, v100
	v_rcp_f32_e32 v101, v101
	v_add_f32_e32 v102, 1.0, v102
	v_add_f32_e32 v103, 1.0, v103
	v_rcp_f32_e32 v102, v102
	v_rcp_f32_e32 v103, v103
	v_pk_mul_f32 v[100:101], v[104:105], v[100:101]
	v_pk_mul_f32 v[94:95], v[94:95], v[174:175] op_sel_hi:[1,0]
	v_pk_mul_f32 v[98:99], v[98:99], v[100:101]
	v_pk_mul_f32 v[100:101], v[106:107], v[102:103]
	v_cvt_pk_bf16_f32 v98, v98, v99
	v_pk_mul_f32 v[100:101], v[116:117], v[100:101]
; __device__ __forceinline__ unsigned cvt_pk_bf16(float lo, float hi) { f32x2 v = {lo, hi}; bf16x2_t b = __builtin_convertvector(v, bf16x2_t); return __builtin_bit_cast(unsigned, b); }
; __device__ __forceinline__ float silu_f(float x) { return x * __builtin_amdgcn_rcpf(1.0f + __builtin_amdgcn_exp2f(-x * LOG2E)); }
;     __device__ __forceinline__ void operator()(const f32x4 (&acc)[2][2][4][2], const Unit& u, int wr, int wc, int fr, int fq) const {
;     ...
;             for (int m = 0; m < 4; ++m) { const int row = row0 + ai * HALF + m * 16; const float r = rs[ai][m];
;                 const f32x4 g0 = acc[ai][0][m][0] * r, g1 = acc[ai][0][m][1] * r, u0 = acc[ai][1][m][0] * r, u1 = acc[ai][1][m][1] * r;
;                 u32x4 w;
;                 w.x = cvt_pk_bf16(silu_f(g0[0]) * u0[0], silu_f(g0[1]) * u0[1]); w.y = cvt_pk_bf16(silu_f(g0[2]) * u0[2], silu_f(g0[3]) * u0[3]);
;                 w.z = cvt_pk_bf16(silu_f(g1[0]) * u1[0], silu_f(g1[1]) * u1[1]); w.w = cvt_pk_bf16(silu_f(g1[2]) * u1[2], silu_f(g1[3]) * u1[3]);
;                 *(u32x4*)(O + (size_t)row * ldo + col0) = w; }
	v_pk_mul_f32 v[84:85], v[84:85], v[174:175] op_sel_hi:[1,0]
	v_cvt_pk_bf16_f32 v99, v100, v101
	v_mad_i64_i32 v[100:101], s[12:13], v164, s45, v[112:113]
	v_lshl_add_u64 v[100:101], v[100:101], 0, v[114:115]
	global_store_dwordx4 v[100:101], v[96:99], off
	v_pk_mul_f32 v[88:89], v[88:89], v[174:175] op_sel_hi:[1,0]
	v_pk_mul_f32 v[86:87], v[86:87], v[174:175] op_sel_hi:[1,0]
	v_pk_mul_f32 v[96:97], v[82:83], v[174:175] op_sel_hi:[1,0]
	v_mul_f32_e32 v82, 0xbfb8aa3b, v92
	v_exp_f32_e32 v98, v82
	v_mul_f32_e32 v82, 0xbfb8aa3b, v93
	v_exp_f32_e32 v99, v82
	v_pk_mul_f32 v[82:83], v[80:81], v[174:175] op_sel_hi:[1,0]
	v_add_f32_e32 v80, 1.0, v98
	v_mul_f32_e32 v98, 0xbfb8aa3b, v94
	v_add_f32_e32 v81, 1.0, v99
	v_mul_f32_e32 v99, 0xbfb8aa3b, v95
	v_exp_f32_e32 v98, v98
	v_exp_f32_e32 v99, v99
	v_rcp_f32_e32 v80, v80
	v_rcp_f32_e32 v81, v81
	v_add_f32_e32 v98, 1.0, v98
	v_add_f32_e32 v99, 1.0, v99
	v_rcp_f32_e32 v98, v98
	v_rcp_f32_e32 v99, v99
	v_pk_mul_f32 v[80:81], v[92:93], v[80:81]
	v_pk_mul_f32 v[90:91], v[90:91], v[174:175] op_sel_hi:[1,0]
	v_pk_mul_f32 v[80:81], v[84:85], v[80:81]
	v_pk_mul_f32 v[84:85], v[94:95], v[98:99]
	v_cvt_pk_bf16_f32 v80, v80, v81
	v_mul_f32_e32 v81, 0xbfb8aa3b, v88
	v_pk_mul_f32 v[84:85], v[86:87], v[84:85]
	v_exp_f32_e32 v86, v81
	v_mul_f32_e32 v81, 0xbfb8aa3b, v89
	v_exp_f32_e32 v87, v81
	v_cvt_pk_bf16_f32 v81, v84, v85
	v_add_f32_e32 v84, 1.0, v86
	v_mul_f32_e32 v86, 0xbfb8aa3b, v90
	v_add_f32_e32 v85, 1.0, v87
	v_mul_f32_e32 v87, 0xbfb8aa3b, v91
	v_exp_f32_e32 v86, v86
	v_exp_f32_e32 v87, v87
	v_rcp_f32_e32 v84, v84
	v_rcp_f32_e32 v85, v85
	v_add_f32_e32 v86, 1.0, v86
	v_add_f32_e32 v87, 1.0, v87
	v_rcp_f32_e32 v86, v86
	v_rcp_f32_e32 v87, v87
	v_pk_mul_f32 v[84:85], v[88:89], v[84:85]
	v_mov_b32_e32 v170, v184
	v_pk_mul_f32 v[76:77], v[76:77], v[170:171] op_sel_hi:[1,0]
	v_pk_mul_f32 v[82:83], v[82:83], v[84:85]
	v_pk_mul_f32 v[84:85], v[90:91], v[86:87]
	v_cvt_pk_bf16_f32 v82, v82, v83
	v_pk_mul_f32 v[84:85], v[96:97], v[84:85]
	v_pk_mul_f32 v[78:79], v[78:79], v[170:171] op_sel_hi:[1,0]
	v_cvt_pk_bf16_f32 v83, v84, v85
	v_mad_i64_i32 v[84:85], s[12:13], v160, s45, v[112:113]
	v_lshl_add_u64 v[84:85], v[84:85], 0, v[114:115]
	global_store_dwordx4 v[84:85], v[80:83], off
	v_pk_mul_f32 v[68:69], v[68:69], v[170:171] op_sel_hi:[1,0]
	v_pk_mul_f32 v[72:73], v[72:73], v[170:171] op_sel_hi:[1,0]
	v_pk_mul_f32 v[80:81], v[66:67], v[170:171] op_sel_hi:[1,0]
	v_mul_f32_e32 v66, 0xbfb8aa3b, v76
	v_exp_f32_e32 v82, v66
	v_mul_f32_e32 v66, 0xbfb8aa3b, v77
	v_exp_f32_e32 v83, v66
	v_pk_mul_f32 v[66:67], v[64:65], v[170:171] op_sel_hi:[1,0]
	v_add_f32_e32 v64, 1.0, v82
	v_mul_f32_e32 v82, 0xbfb8aa3b, v78
	v_add_f32_e32 v65, 1.0, v83
	v_mul_f32_e32 v83, 0xbfb8aa3b, v79
	v_exp_f32_e32 v82, v82
	v_exp_f32_e32 v83, v83
	v_rcp_f32_e32 v64, v64
	v_rcp_f32_e32 v65, v65
	v_add_f32_e32 v82, 1.0, v82
	v_add_f32_e32 v83, 1.0, v83
	v_rcp_f32_e32 v82, v82
	v_rcp_f32_e32 v83, v83
	v_pk_mul_f32 v[64:65], v[76:77], v[64:65]
	v_pk_mul_f32 v[70:71], v[70:71], v[170:171] op_sel_hi:[1,0]
	v_pk_mul_f32 v[64:65], v[68:69], v[64:65]
	v_pk_mul_f32 v[68:69], v[78:79], v[82:83]
	v_cvt_pk_bf16_f32 v64, v64, v65
	v_mul_f32_e32 v65, 0xbfb8aa3b, v72
	v_pk_mul_f32 v[68:69], v[70:71], v[68:69]
	v_exp_f32_e32 v70, v65
	v_mul_f32_e32 v65, 0xbfb8aa3b, v73
	v_exp_f32_e32 v71, v65
	v_pk_mul_f32 v[74:75], v[74:75], v[170:171] op_sel_hi:[1,0]
	v_cvt_pk_bf16_f32 v65, v68, v69
	v_add_f32_e32 v68, 1.0, v70
	v_add_f32_e32 v69, 1.0, v71
	v_mul_f32_e32 v70, 0xbfb8aa3b, v74
	v_mul_f32_e32 v71, 0xbfb8aa3b, v75
	v_exp_f32_e32 v70, v70
	v_exp_f32_e32 v71, v71
	v_rcp_f32_e32 v68, v68
	v_rcp_f32_e32 v69, v69
	v_add_f32_e32 v70, 1.0, v70
	v_add_f32_e32 v71, 1.0, v71
	v_rcp_f32_e32 v70, v70
	v_rcp_f32_e32 v71, v71
	v_pk_mul_f32 v[68:69], v[72:73], v[68:69]
	v_mov_b32_e32 v166, v185
	v_pk_mul_f32 v[60:61], v[60:61], v[166:167] op_sel_hi:[1,0]
	v_pk_mul_f32 v[66:67], v[66:67], v[68:69]
	v_pk_mul_f32 v[68:69], v[74:75], v[70:71]
	v_cvt_pk_bf16_f32 v66, v66, v67
	v_pk_mul_f32 v[68:69], v[80:81], v[68:69]
	v_pk_mul_f32 v[62:63], v[62:63], v[166:167] op_sel_hi:[1,0]
	v_cvt_pk_bf16_f32 v67, v68, v69
	v_mad_i64_i32 v[68:69], s[12:13], v156, s45, v[112:113]
	v_lshl_add_u64 v[68:69], v[68:69], 0, v[114:115]
	global_store_dwordx4 v[68:69], v[64:67], off
	v_pk_mul_f32 v[52:53], v[52:53], v[166:167] op_sel_hi:[1,0]
	v_pk_mul_f32 v[56:57], v[56:57], v[166:167] op_sel_hi:[1,0]
	v_pk_mul_f32 v[64:65], v[50:51], v[166:167] op_sel_hi:[1,0]
	v_mul_f32_e32 v50, 0xbfb8aa3b, v60
	v_exp_f32_e32 v66, v50
	v_mul_f32_e32 v50, 0xbfb8aa3b, v61
	v_exp_f32_e32 v67, v50
	v_pk_mul_f32 v[50:51], v[48:49], v[166:167] op_sel_hi:[1,0]
	v_add_f32_e32 v48, 1.0, v66
	v_mul_f32_e32 v66, 0xbfb8aa3b, v62
	v_add_f32_e32 v49, 1.0, v67
	v_mul_f32_e32 v67, 0xbfb8aa3b, v63
	v_exp_f32_e32 v66, v66
	v_exp_f32_e32 v67, v67
	v_rcp_f32_e32 v48, v48
	v_rcp_f32_e32 v49, v49
	v_add_f32_e32 v66, 1.0, v66
	v_add_f32_e32 v67, 1.0, v67
	v_rcp_f32_e32 v66, v66
	v_rcp_f32_e32 v67, v67
	v_pk_mul_f32 v[48:49], v[60:61], v[48:49]
	v_pk_mul_f32 v[54:55], v[54:55], v[166:167] op_sel_hi:[1,0]
	v_pk_mul_f32 v[48:49], v[52:53], v[48:49]
	v_pk_mul_f32 v[52:53], v[62:63], v[66:67]
	v_cvt_pk_bf16_f32 v48, v48, v49
	v_mul_f32_e32 v49, 0xbfb8aa3b, v56
	v_pk_mul_f32 v[52:53], v[54:55], v[52:53]
	v_exp_f32_e32 v54, v49
	v_mul_f32_e32 v49, 0xbfb8aa3b, v57
	v_exp_f32_e32 v55, v49
	v_pk_mul_f32 v[58:59], v[58:59], v[166:167] op_sel_hi:[1,0]
	v_cvt_pk_bf16_f32 v49, v52, v53
	v_add_f32_e32 v52, 1.0, v54
	v_add_f32_e32 v53, 1.0, v55
	v_mul_f32_e32 v54, 0xbfb8aa3b, v58
	v_mul_f32_e32 v55, 0xbfb8aa3b, v59
	v_exp_f32_e32 v54, v54
	v_exp_f32_e32 v55, v55
; __device__ __forceinline__ unsigned cvt_pk_bf16(float lo, float hi) { f32x2 v = {lo, hi}; bf16x2_t b = __builtin_convertvector(v, bf16x2_t); return __builtin_bit_cast(unsigned, b); }
; __device__ __forceinline__ float silu_f(float x) { return x * __builtin_amdgcn_rcpf(1.0f + __builtin_amdgcn_exp2f(-x * LOG2E)); }
; #define PG8_BAR __builtin_amdgcn_s_barrier()
;     __device__ __forceinline__ void operator()(const f32x4 (&acc)[2][2][4][2], const Unit& u, int wr, int wc, int fr, int fq) const {
;     ...
;             for (int m = 0; m < 4; ++m) { const int row = row0 + ai * HALF + m * 16; const float r = rs[ai][m];
;                 const f32x4 g0 = acc[ai][0][m][0] * r, g1 = acc[ai][0][m][1] * r, u0 = acc[ai][1][m][0] * r, u1 = acc[ai][1][m][1] * r;
;                 u32x4 w;
;                 w.x = cvt_pk_bf16(silu_f(g0[0]) * u0[0], silu_f(g0[1]) * u0[1]); w.y = cvt_pk_bf16(silu_f(g0[2]) * u0[2], silu_f(g0[3]) * u0[3]);
;                 w.z = cvt_pk_bf16(silu_f(g1[0]) * u1[0], silu_f(g1[1]) * u1[1]); w.w = cvt_pk_bf16(silu_f(g1[2]) * u1[2], silu_f(g1[3]) * u1[3]);
;                 *(u32x4*)(O + (size_t)row * ldo + col0) = w; }
; template <class Epi, class Sched, bool ALIGN_EPI = false, bool SP2 = false>
; __device__ __forceinline__ void gemm_phase(PG8_LAS unsigned char* lds, const Gemm g, const Sched& S, const Epi& E) {
;     ...
;         if constexpr (!Epi::AFTER_DRAIN) { E(acc, cur, wr, wc, fr, fq); S.done(cur); }
;         if (!has_next) break;
; #pragma unroll
;         for (int a = 0; a < 2; ++a)
; #pragma unroll
;             for (int b = 0; b < 2; ++b)
; #pragma unroll
;                 for (int m = 0; m < 4; ++m)
; #pragma unroll
;                     for (int n = 0; n < 2; ++n) acc[a][b][m][n] = (f32x4){0.f, 0.f, 0.f, 0.f};
;         cur = nxt; cA = nA; cB = nB; ++ui;
;         if constexpr (ALIGN_EPI) { if (wr == 1) PG8_BAR; }
	v_rcp_f32_e32 v52, v52
	v_rcp_f32_e32 v53, v53
	v_add_f32_e32 v54, 1.0, v54
	v_add_f32_e32 v55, 1.0, v55
	v_rcp_f32_e32 v54, v54
	v_rcp_f32_e32 v55, v55
	v_pk_mul_f32 v[52:53], v[56:57], v[52:53]
	v_mov_b32_e32 v162, v161
	v_pk_mul_f32 v[44:45], v[44:45], v[162:163] op_sel_hi:[1,0]
	v_pk_mul_f32 v[50:51], v[50:51], v[52:53]
	v_pk_mul_f32 v[52:53], v[58:59], v[54:55]
	v_cvt_pk_bf16_f32 v50, v50, v51
	v_pk_mul_f32 v[52:53], v[64:65], v[52:53]
	v_pk_mul_f32 v[46:47], v[46:47], v[162:163] op_sel_hi:[1,0]
	v_cvt_pk_bf16_f32 v51, v52, v53
	v_mad_i64_i32 v[52:53], s[12:13], v152, s45, v[112:113]
	v_lshl_add_u64 v[52:53], v[52:53], 0, v[114:115]
	global_store_dwordx4 v[52:53], v[48:51], off
	v_pk_mul_f32 v[36:37], v[36:37], v[162:163] op_sel_hi:[1,0]
	v_pk_mul_f32 v[40:41], v[40:41], v[162:163] op_sel_hi:[1,0]
	v_pk_mul_f32 v[48:49], v[34:35], v[162:163] op_sel_hi:[1,0]
	v_mul_f32_e32 v34, 0xbfb8aa3b, v44
	v_exp_f32_e32 v50, v34
	v_mul_f32_e32 v34, 0xbfb8aa3b, v45
	v_exp_f32_e32 v51, v34
	v_pk_mul_f32 v[34:35], v[32:33], v[162:163] op_sel_hi:[1,0]
	v_add_f32_e32 v32, 1.0, v50
	v_mul_f32_e32 v50, 0xbfb8aa3b, v46
	v_add_f32_e32 v33, 1.0, v51
	v_mul_f32_e32 v51, 0xbfb8aa3b, v47
	v_exp_f32_e32 v50, v50
	v_exp_f32_e32 v51, v51
	v_rcp_f32_e32 v32, v32
	v_rcp_f32_e32 v33, v33
	v_add_f32_e32 v50, 1.0, v50
	v_add_f32_e32 v51, 1.0, v51
	v_rcp_f32_e32 v50, v50
	v_rcp_f32_e32 v51, v51
	v_pk_mul_f32 v[32:33], v[44:45], v[32:33]
	v_pk_mul_f32 v[38:39], v[38:39], v[162:163] op_sel_hi:[1,0]
	v_pk_mul_f32 v[32:33], v[36:37], v[32:33]
	v_pk_mul_f32 v[36:37], v[46:47], v[50:51]
	v_cvt_pk_bf16_f32 v32, v32, v33
	v_mul_f32_e32 v33, 0xbfb8aa3b, v40
	v_pk_mul_f32 v[36:37], v[38:39], v[36:37]
	v_exp_f32_e32 v38, v33
	v_mul_f32_e32 v33, 0xbfb8aa3b, v41
	v_exp_f32_e32 v39, v33
	v_pk_mul_f32 v[42:43], v[42:43], v[162:163] op_sel_hi:[1,0]
	v_cvt_pk_bf16_f32 v33, v36, v37
	v_add_f32_e32 v36, 1.0, v38
	v_add_f32_e32 v37, 1.0, v39
	v_mul_f32_e32 v38, 0xbfb8aa3b, v42
	v_mul_f32_e32 v39, 0xbfb8aa3b, v43
	v_exp_f32_e32 v38, v38
	v_exp_f32_e32 v39, v39
	v_rcp_f32_e32 v36, v36
	v_rcp_f32_e32 v37, v37
	v_add_f32_e32 v38, 1.0, v38
	v_add_f32_e32 v39, 1.0, v39
	v_rcp_f32_e32 v38, v38
	v_rcp_f32_e32 v39, v39
	v_pk_mul_f32 v[36:37], v[40:41], v[36:37]
	v_mov_b32_e32 v158, v186
	v_pk_mul_f32 v[28:29], v[28:29], v[158:159] op_sel_hi:[1,0]
	v_pk_mul_f32 v[34:35], v[34:35], v[36:37]
	v_pk_mul_f32 v[36:37], v[42:43], v[38:39]
	v_cvt_pk_bf16_f32 v34, v34, v35
	v_pk_mul_f32 v[36:37], v[48:49], v[36:37]
	v_pk_mul_f32 v[30:31], v[30:31], v[158:159] op_sel_hi:[1,0]
	v_cvt_pk_bf16_f32 v35, v36, v37
	v_mad_i64_i32 v[36:37], s[12:13], v150, s45, v[112:113]
	v_lshl_add_u64 v[36:37], v[36:37], 0, v[114:115]
	global_store_dwordx4 v[36:37], v[32:35], off
	v_pk_mul_f32 v[20:21], v[20:21], v[158:159] op_sel_hi:[1,0]
	v_pk_mul_f32 v[24:25], v[24:25], v[158:159] op_sel_hi:[1,0]
	v_pk_mul_f32 v[32:33], v[18:19], v[158:159] op_sel_hi:[1,0]
	v_mul_f32_e32 v18, 0xbfb8aa3b, v28
	v_exp_f32_e32 v34, v18
	v_mul_f32_e32 v18, 0xbfb8aa3b, v29
	v_exp_f32_e32 v35, v18
	v_pk_mul_f32 v[18:19], v[16:17], v[158:159] op_sel_hi:[1,0]
	v_add_f32_e32 v16, 1.0, v34
	v_mul_f32_e32 v34, 0xbfb8aa3b, v30
	v_add_f32_e32 v17, 1.0, v35
	v_mul_f32_e32 v35, 0xbfb8aa3b, v31
	v_exp_f32_e32 v34, v34
	v_exp_f32_e32 v35, v35
	v_rcp_f32_e32 v16, v16
	v_rcp_f32_e32 v17, v17
	v_add_f32_e32 v34, 1.0, v34
	v_add_f32_e32 v35, 1.0, v35
	v_rcp_f32_e32 v34, v34
	v_rcp_f32_e32 v35, v35
	v_pk_mul_f32 v[16:17], v[28:29], v[16:17]
	v_pk_mul_f32 v[22:23], v[22:23], v[158:159] op_sel_hi:[1,0]
	v_pk_mul_f32 v[16:17], v[20:21], v[16:17]
	v_pk_mul_f32 v[20:21], v[30:31], v[34:35]
	v_cvt_pk_bf16_f32 v16, v16, v17
	v_mul_f32_e32 v17, 0xbfb8aa3b, v24
	v_pk_mul_f32 v[20:21], v[22:23], v[20:21]
	v_exp_f32_e32 v22, v17
	v_mul_f32_e32 v17, 0xbfb8aa3b, v25
	v_exp_f32_e32 v23, v17
	v_pk_mul_f32 v[26:27], v[26:27], v[158:159] op_sel_hi:[1,0]
	v_cvt_pk_bf16_f32 v17, v20, v21
	v_add_f32_e32 v20, 1.0, v22
	v_add_f32_e32 v21, 1.0, v23
	v_mul_f32_e32 v22, 0xbfb8aa3b, v26
	v_mul_f32_e32 v23, 0xbfb8aa3b, v27
	v_exp_f32_e32 v22, v22
	v_exp_f32_e32 v23, v23
	v_rcp_f32_e32 v20, v20
	v_rcp_f32_e32 v21, v21
	v_add_f32_e32 v22, 1.0, v22
	v_add_f32_e32 v23, 1.0, v23
	v_rcp_f32_e32 v22, v22
	v_rcp_f32_e32 v23, v23
	v_pk_mul_f32 v[20:21], v[24:25], v[20:21]
	v_mov_b32_e32 v154, v187
	v_pk_mul_f32 v[12:13], v[12:13], v[154:155] op_sel_hi:[1,0]
.Lrc7_join:
	v_pk_mul_f32 v[18:19], v[18:19], v[20:21]
	v_pk_mul_f32 v[20:21], v[26:27], v[22:23]
	v_cvt_pk_bf16_f32 v18, v18, v19
	v_pk_mul_f32 v[20:21], v[32:33], v[20:21]
	v_pk_mul_f32 v[14:15], v[14:15], v[154:155] op_sel_hi:[1,0]
	v_cvt_pk_bf16_f32 v19, v20, v21
	v_mad_i64_i32 v[20:21], s[12:13], v148, s45, v[112:113]
	v_lshl_add_u64 v[20:21], v[20:21], 0, v[114:115]
	global_store_dwordx4 v[20:21], v[16:19], off
	v_pk_mul_f32 v[4:5], v[4:5], v[154:155] op_sel_hi:[1,0]
	v_pk_mul_f32 v[8:9], v[8:9], v[154:155] op_sel_hi:[1,0]
	v_pk_mul_f32 v[16:17], v[2:3], v[154:155] op_sel_hi:[1,0]
	v_mul_f32_e32 v2, 0xbfb8aa3b, v12
	v_exp_f32_e32 v18, v2
	v_mul_f32_e32 v2, 0xbfb8aa3b, v13
	v_exp_f32_e32 v19, v2
	v_pk_mul_f32 v[2:3], v[0:1], v[154:155] op_sel_hi:[1,0]
	v_add_f32_e32 v0, 1.0, v18
	v_mul_f32_e32 v18, 0xbfb8aa3b, v14
	v_add_f32_e32 v1, 1.0, v19
	v_mul_f32_e32 v19, 0xbfb8aa3b, v15
	v_exp_f32_e32 v18, v18
	v_exp_f32_e32 v19, v19
	v_rcp_f32_e32 v0, v0
	v_rcp_f32_e32 v1, v1
	v_add_f32_e32 v18, 1.0, v18
	v_add_f32_e32 v19, 1.0, v19
	v_rcp_f32_e32 v18, v18
	v_rcp_f32_e32 v19, v19
	v_pk_mul_f32 v[0:1], v[12:13], v[0:1]
	v_pk_mul_f32 v[6:7], v[6:7], v[154:155] op_sel_hi:[1,0]
	v_pk_mul_f32 v[0:1], v[4:5], v[0:1]
	v_pk_mul_f32 v[4:5], v[14:15], v[18:19]
	v_cvt_pk_bf16_f32 v0, v0, v1
	v_mul_f32_e32 v1, 0xbfb8aa3b, v8
	v_pk_mul_f32 v[4:5], v[6:7], v[4:5]
	v_exp_f32_e32 v6, v1
	v_mul_f32_e32 v1, 0xbfb8aa3b, v9
	v_exp_f32_e32 v7, v1
	v_pk_mul_f32 v[10:11], v[10:11], v[154:155] op_sel_hi:[1,0]
	v_cvt_pk_bf16_f32 v1, v4, v5
	v_add_f32_e32 v4, 1.0, v6
	v_add_f32_e32 v5, 1.0, v7
	v_mul_f32_e32 v6, 0xbfb8aa3b, v10
	v_mul_f32_e32 v7, 0xbfb8aa3b, v11
	v_exp_f32_e32 v6, v6
	v_exp_f32_e32 v7, v7
	v_rcp_f32_e32 v4, v4
	v_rcp_f32_e32 v5, v5
	v_add_f32_e32 v6, 1.0, v6
	v_add_f32_e32 v7, 1.0, v7
	v_rcp_f32_e32 v6, v6
	v_rcp_f32_e32 v7, v7
	v_pk_mul_f32 v[4:5], v[8:9], v[4:5]
	s_nop 0
	v_pk_mul_f32 v[2:3], v[2:3], v[4:5]
	v_pk_mul_f32 v[4:5], v[10:11], v[6:7]
	v_cvt_pk_bf16_f32 v2, v2, v3
	v_pk_mul_f32 v[4:5], v[16:17], v[4:5]
	s_nop 0
	v_cvt_pk_bf16_f32 v3, v4, v5
	v_mad_i64_i32 v[4:5], s[12:13], v146, s45, v[112:113]
	v_lshl_add_u64 v[4:5], v[4:5], 0, v[114:115]
	global_store_dwordx4 v[4:5], v[0:3], off
	s_cbranch_vccnz .LBB0_1021
	s_andn2_b64 vcc, exec, s[8:9]
	s_cbranch_vccnz .LBB0_1020
	s_barrier
	s_branch .LBB0_1020
